# attention: remaining cross-lane shuffles (RMS-norm quad sums, row max / row sum in the peeled steps) done with DPP quad_perm and v_permlane16/32_swap instead of ds_bpermute
# baseline (speedup 1.0000x reference)
; __device__ __forceinline__ float bflo(unsigned u) { return __uint_as_float(u << 16); }
; __device__ __forceinline__ float bfhi(unsigned u) { return __uint_as_float(u & 0xffff0000u); }
; __device__ __forceinline__ float shx(float v, int mask, int lane) { return __int_as_float(__builtin_amdgcn_ds_bpermute((lane ^ mask) << 2, __float_as_int(v))); }
; __device__ __forceinline__ void unpack16(const u32x4& a, const u32x4& b, float (&x)[16]) {
;     x[0] = bflo(a.x); x[1] = bfhi(a.x); x[2] = bflo(a.y); x[3] = bfhi(a.y); x[4] = bflo(a.z); x[5] = bfhi(a.z); x[6] = bflo(a.w); x[7] = bfhi(a.w);
;     x[8] = bflo(b.x); x[9] = bfhi(b.x); x[10] = bflo(b.y); x[11] = bfhi(b.y); x[12] = bflo(b.z); x[13] = bfhi(b.z); x[14] = bflo(b.w); x[15] = bfhi(b.w);
; }
; __device__ __forceinline__ void qk_prep_store(u32x4 a, u32x4 b, const float* gain, int sub, int pos, float scale, bf16_t* dst, int lane) {
;     float x[16]; unpack16(a, b, x);
;     float ss = 0.f;
; #pragma unroll
;     for (int i = 0; i < 16; ++i) ss += x[i] * x[i];
;     ss += shx(ss, 1, lane); ss += shx(ss, 2, lane);
;     const float r = rsqrtf(ss * (1.0f / 64.0f) + EPS);
; #pragma unroll
;     for (int i = 0; i < 16; ++i) x[i] = x[i] * r * gain[sub * 16 + i];
.LBB0_824:
	global_load_dwordx4 v[74:77], v[68:69], off
	global_load_dwordx4 v[88:91], v[68:69], off offset:16
	global_load_dwordx4 v[158:161], v[68:69], off offset:32
	global_load_dwordx4 v[162:165], v[68:69], off offset:48
	s_waitcnt vmcnt(6)
	v_lshlrev_b32_e32 v82, 16, v62
	v_and_b32_e32 v83, 0xffff0000, v62
	v_lshlrev_b32_e32 v62, 16, v63
	v_and_b32_e32 v63, 0xffff0000, v63
	v_pk_mul_f32 v[168:169], v[82:83], v[82:83]
	v_pk_mul_f32 v[172:173], v[62:63], v[62:63]
	v_add_f32_e32 v79, v168, v169
	v_lshlrev_b32_e32 v166, 16, v64
	v_and_b32_e32 v167, 0xffff0000, v64
	v_add_f32_e32 v79, v172, v79
	v_pk_mul_f32 v[176:177], v[166:167], v[166:167]
	v_add_f32_e32 v79, v173, v79
	v_add_f32_e32 v79, v176, v79
	v_lshlrev_b32_e32 v180, 16, v65
	v_add_f32_e32 v79, v177, v79
	v_and_b32_e32 v78, 0xffff0000, v65
	v_lshlrev_b32_e32 v92, 16, v58
	v_and_b32_e32 v93, 0xffff0000, v58
	v_fmac_f32_e32 v79, v180, v180
	v_pk_mul_f32 v[170:171], v[92:93], v[92:93]
	v_fmac_f32_e32 v79, v78, v78
	v_lshlrev_b32_e32 v58, 16, v59
	v_and_b32_e32 v59, 0xffff0000, v59
	v_add_f32_e32 v79, v170, v79
	v_pk_mul_f32 v[174:175], v[58:59], v[58:59]
	v_add_f32_e32 v79, v171, v79
	v_lshlrev_b32_e32 v64, 16, v60
	v_and_b32_e32 v65, 0xffff0000, v60
	v_add_f32_e32 v79, v174, v79
	v_pk_mul_f32 v[178:179], v[64:65], v[64:65]
	v_add_f32_e32 v79, v175, v79
	v_and_b32_e32 v80, 0xffff0000, v61
	v_lshlrev_b32_e32 v81, 16, v61
	v_add_f32_e32 v79, v178, v79
	v_pk_mul_f32 v[60:61], v[80:81], v[80:81]
	v_add_f32_e32 v79, v179, v79
	v_add_f32_e32 v61, v61, v79
	v_add_f32_e32 v60, v60, v61
	s_nop 1
	v_mov_b32_dpp v61, v60 quad_perm:[1,0,3,2] row_mask:0xf bank_mask:0xf
	s_mov_b32 s2, 0x800000
	v_mov_b32_e32 v79, v80
	s_waitcnt lgkmcnt(0)
	v_add_f32_e32 v60, v60, v61
	s_nop 1
	v_mov_b32_dpp v61, v60 quad_perm:[2,3,0,1] row_mask:0xf bank_mask:0xf
	s_waitcnt lgkmcnt(0)
	v_add_f32_e32 v60, v60, v61
	v_fmamk_f32 v60, v60, 0x3c800000, v205
	v_mul_f32_e32 v61, 0x4b800000, v60
	v_cmp_gt_f32_e32 vcc, s2, v60
	s_nop 1
	v_cndmask_b32_e32 v60, v60, v61, vcc
	v_rsq_f32_e32 v60, v60
	s_nop 0
	v_mul_f32_e32 v61, 0x45800000, v60
	v_cndmask_b32_e32 v60, v60, v61, vcc
	v_pk_mul_f32 v[82:83], v[60:61], v[82:83] op_sel_hi:[0,1]
	v_pk_mul_f32 v[62:63], v[60:61], v[62:63] op_sel_hi:[0,1]
	v_pk_mul_f32 v[166:167], v[60:61], v[166:167] op_sel_hi:[0,1]
	v_mul_f32_e32 v61, v60, v180
	v_pk_mul_f32 v[58:59], v[60:61], v[58:59] op_sel_hi:[0,1]
	v_pk_mul_f32 v[64:65], v[60:61], v[64:65] op_sel_hi:[0,1]
	v_mul_f32_e32 v170, v60, v81
	v_pk_mul_f32 v[92:93], v[60:61], v[92:93] op_sel_hi:[0,1]
	v_pk_mul_f32 v[168:169], v[60:61], v[78:79] op_sel_hi:[0,1]
	s_waitcnt vmcnt(3)
	v_pk_mul_f32 v[82:83], v[74:75], v[82:83]
	s_waitcnt vmcnt(2)
	v_mul_f32_e32 v74, v90, v61
	s_waitcnt vmcnt(1)
	v_pk_mul_f32 v[60:61], v[58:59], v[160:161]
	s_waitcnt vmcnt(0)
	v_pk_mul_f32 v[58:59], v[64:65], v[162:163]
	v_mul_f32_e32 v64, v170, v164
	v_mov_b32_e32 v164, v91
	v_pk_mul_f32 v[80:81], v[76:77], v[62:63]
	v_pk_mul_f32 v[78:79], v[88:89], v[166:167]
	v_pk_mul_f32 v[62:63], v[158:159], v[92:93]
	v_pk_mul_f32 v[76:77], v[164:165], v[168:169]
	s_and_saveexec_b64 s[2:3], s[4:5]
	s_cbranch_execz .LBB0_826
; __device__ __forceinline__ float2 twid(float turns) { return make_float2(__builtin_amdgcn_cosf(turns), __builtin_amdgcn_sinf(turns)); }
; __device__ __forceinline__ void qk_prep_store(u32x4 a, u32x4 b, const float* gain, int sub, int pos, float scale, bf16_t* dst, int lane) {
;     ...
;     if (sub == 0) {
;         const float ihi[8] = {(float)(1.0 / 3.14159265358979323846), (float)(0.19392274474868576 / 3.14159265358979323846), (float)(0.03760603093086393 / 3.14159265358979323846), (float)(0.007292664737217109 / 3.14159265358979323846),
;                               (float)(0.001414213562373095 / 3.14159265358979323846), (float)(0.0002742481756762073 / 3.14159265358979323846), (float)(5.318295896944988e-05 / 3.14159265358979323846), (float)(1.031338537721246e-05 / 3.14159265358979323846)};
;         const float ilo[8] = {(float)(1.0 / 3.14159265358979323846 - (double)(float)(1.0 / 3.14159265358979323846)), (float)(0.19392274474868576 / 3.14159265358979323846 - (double)(float)(0.19392274474868576 / 3.14159265358979323846)),
;                               (float)(0.03760603093086393 / 3.14159265358979323846 - (double)(float)(0.03760603093086393 / 3.14159265358979323846)), (float)(0.007292664737217109 / 3.14159265358979323846 - (double)(float)(0.007292664737217109 / 3.14159265358979323846)),
;                               (float)(0.001414213562373095 / 3.14159265358979323846 - (double)(float)(0.001414213562373095 / 3.14159265358979323846)), (float)(0.0002742481756762073 / 3.14159265358979323846 - (double)(float)(0.0002742481756762073 / 3.14159265358979323846)),
;                               (float)(5.318295896944988e-05 / 3.14159265358979323846 - (double)(float)(5.318295896944988e-05 / 3.14159265358979323846)), (float)(1.031338537721246e-05 / 3.14159265358979323846 - (double)(float)(1.031338537721246e-05 / 3.14159265358979323846))};
; #pragma unroll
;         for (int j = 0; j < 8; ++j) {
;             const float fp = (float)pos, ph = fp * ihi[j], pe = __builtin_fmaf(fp, ihi[j], -ph) + fp * ilo[j];
;             const float red = (ph - 2.0f * rintf(0.5f * ph)) + pe;
;             const float2 cs = twid(0.5f * red); const float c = cs.x, s = cs.y;
;             const float x1 = x[j], x2 = x[8 + j];
;             x[j] = x1 * c - x2 * s; x[8 + j] = x2 * c + x1 * s;
;         }
;     }
	v_cvt_f32_i32_e32 v88, v87
	s_mov_b32 s16, 0x3ea2f983
	s_mov_b32 s15, 0x3d7cd601
	v_readlane_b32 s36, v254, 14
	v_mul_f32_e32 v65, 0x3ea2f983, v88
	v_mul_f32_e32 v87, 0.5, v65
	v_fma_f32 v75, v88, s16, -v65
	v_rndne_f32_e32 v87, v87
	v_fmac_f32_e32 v75, 0x325c9c88, v88
	v_fmac_f32_e32 v65, -2.0, v87
	v_add_f32_e32 v65, v75, v65
	v_mul_f32_e32 v65, 0.5, v65
	v_mul_f32_e32 v159, 0x3d7cd601, v88
	v_cos_f32_e32 v90, v65
	v_sin_f32_e32 v92, v65
	v_mul_f32_e32 v65, 0.5, v159
	s_mov_b32 s16, 0xb045cd43
	v_fma_f32 v158, v88, s15, -v159
	v_rndne_f32_e32 v89, v65
	s_mov_b32 s17, -2.0
	v_pk_fma_f32 v[158:159], v[88:89], s[16:17], v[158:159]
	s_mov_b32 s15, 0x3c441f60
	v_add_f32_e32 v65, v158, v159
	v_mul_f32_e32 v65, 0.5, v65
	v_sin_f32_e32 v93, v65
	v_cos_f32_e32 v91, v65
	v_mul_f32_e32 v65, 0x3c441f60, v88
	v_fma_f32 v75, v88, s15, -v65
	v_pk_mul_f32 v[158:159], v[92:93], v[62:63]
	v_fmac_f32_e32 v75, 0x2fe5870b, v88
	v_pk_fma_f32 v[158:159], v[90:91], v[82:83], v[158:159] neg_lo:[0,0,1] neg_hi:[0,0,1]
	v_pk_mul_f32 v[82:83], v[92:93], v[82:83]
	v_mul_f32_e32 v93, 0x3b182169, v88
	v_pk_fma_f32 v[62:63], v[90:91], v[62:63], v[82:83]
	v_mul_f32_e32 v82, 0.5, v65
	v_rndne_f32_e32 v82, v82
	v_fmac_f32_e32 v65, -2.0, v82
	v_add_f32_e32 v65, v75, v65
	v_mul_f32_e32 v65, 0.5, v65
	v_cos_f32_e32 v82, v65
	v_sin_f32_e32 v90, v65
	s_mov_b32 s15, 0x3b182169
	v_mul_f32_e32 v65, 0.5, v93
	v_readlane_b32 s37, v254, 15
	v_fma_f32 v92, v88, s15, -v93
	v_rndne_f32_e32 v89, v65
	s_mov_b32 s37, s17
	v_pk_fma_f32 v[92:93], v[88:89], s[36:37], v[92:93]
	s_mov_b32 s16, s36
	v_add_f32_e32 v65, v92, v93
	v_mul_f32_e32 v65, 0.5, v65
	v_cos_f32_e32 v83, v65
	v_sin_f32_e32 v91, v65
	v_writelane_b32 v254, s16, 14
	s_mov_b32 s15, 0x39ec0335
	v_pk_mul_f32 v[92:93], v[90:91], v[60:61]
	v_writelane_b32 v254, s17, 15
	v_pk_mul_f32 v[60:61], v[82:83], v[60:61]
	v_pk_fma_f32 v[92:93], v[82:83], v[80:81], v[92:93] neg_lo:[0,0,1] neg_hi:[0,0,1]
	v_pk_fma_f32 v[60:61], v[90:91], v[80:81], v[60:61]
	v_mul_f32_e32 v81, 0x39ec0335, v88
	v_readlane_b32 s36, v254, 16
	v_mul_f32_e32 v65, 0.5, v81
	v_readlane_b32 s37, v254, 17
	v_fma_f32 v80, v88, s15, -v81
	v_rndne_f32_e32 v89, v65
	s_mov_b32 s37, s17
	s_mov_b32 s16, s36
	v_pk_fma_f32 v[80:81], v[88:89], s[36:37], v[80:81]
	v_writelane_b32 v254, s16, 16
	v_add_f32_e32 v65, v80, v81
	v_mul_f32_e32 v65, 0.5, v65
	v_writelane_b32 v254, s17, 17
	v_mul_f32_e32 v91, 0x38b712a2, v88
	v_cos_f32_e32 v80, v65
	v_sin_f32_e32 v82, v65
	s_mov_b32 s15, 0x38b712a2
	v_mul_f32_e32 v65, 0.5, v91
	v_readlane_b32 s36, v254, 18
	v_fma_f32 v90, v88, s15, -v91
	v_rndne_f32_e32 v89, v65
	s_mov_b32 s16, s36
	v_pk_fma_f32 v[90:91], v[88:89], s[16:17], v[90:91]
	s_mov_b32 s15, 0x378e0206
	v_add_f32_e32 v65, v90, v91
	v_mul_f32_e32 v65, 0.5, v65
	v_cos_f32_e32 v81, v65
	v_sin_f32_e32 v83, v65
	v_mul_f32_e32 v65, 0x378e0206, v88
	v_fma_f32 v75, v88, s15, -v65
	v_fmac_f32_e32 v75, 0x2a947bf1, v88
	v_pk_mul_f32 v[90:91], v[82:83], v[58:59]
	v_pk_mul_f32 v[58:59], v[80:81], v[58:59]
	v_pk_fma_f32 v[90:91], v[80:81], v[78:79], v[90:91] neg_lo:[0,0,1] neg_hi:[0,0,1]
	v_pk_fma_f32 v[58:59], v[82:83], v[78:79], v[58:59]
	v_mul_f32_e32 v78, 0.5, v65
	v_rndne_f32_e32 v78, v78
	v_fmac_f32_e32 v65, -2.0, v78
	v_add_f32_e32 v65, v75, v65
	v_mul_f32_e32 v65, 0.5, v65
	v_cos_f32_e32 v78, v65
	v_sin_f32_e32 v80, v65
	v_mul_f32_e32 v65, 0x365c4efa, v88
	s_mov_b32 s15, 0x365c4efa
	v_mul_f32_e32 v79, 0.5, v65
	v_fma_f32 v75, v88, s15, -v65
	v_rndne_f32_e32 v79, v79
	v_fmac_f32_e32 v75, 0x28c5eb61, v88
	v_fmac_f32_e32 v65, -2.0, v79
	v_add_f32_e32 v65, v75, v65
	v_mul_f32_e32 v65, 0.5, v65
	v_sin_f32_e32 v81, v65
	v_cos_f32_e32 v79, v65
	v_mov_b32_e32 v65, v77
	v_mul_f32_e32 v82, v78, v64
	v_mov_b32_e32 v75, v76
	v_pk_mul_f32 v[64:65], v[80:81], v[64:65]
	v_mul_f32_e32 v160, v80, v74
	v_pk_fma_f32 v[74:75], v[78:79], v[74:75], v[64:65] neg_lo:[0,0,1] neg_hi:[0,0,1]
	v_mov_b32_e32 v78, v81
	v_pk_mul_f32 v[64:65], v[78:79], v[76:77]
	v_readlane_b32 s37, v254, 19
	v_mov_b32_e32 v161, v64
	v_mov_b32_e32 v83, v65
	v_writelane_b32 v254, s36, 18
	v_pk_add_f32 v[64:65], v[160:161], v[82:83]
	v_mov_b32_e32 v82, v158
	v_writelane_b32 v254, s37, 19
	v_mov_b32_e32 v83, v159
	v_mov_b32_e32 v80, v92
	v_mov_b32_e32 v81, v93
	v_mov_b32_e32 v78, v90
	v_mov_b32_e32 v79, v91
	v_mov_b32_e32 v76, v75
	v_mov_b32_e32 v77, v65

; __device__ __forceinline__ float bflo(unsigned u) { return __uint_as_float(u << 16); }
; __device__ __forceinline__ float bfhi(unsigned u) { return __uint_as_float(u & 0xffff0000u); }
; __device__ __forceinline__ float shx(float v, int mask, int lane) { return __int_as_float(__builtin_amdgcn_ds_bpermute((lane ^ mask) << 2, __float_as_int(v))); }
; __device__ __forceinline__ void unpack16(const u32x4& a, const u32x4& b, float (&x)[16]) {
;     x[0] = bflo(a.x); x[1] = bfhi(a.x); x[2] = bflo(a.y); x[3] = bfhi(a.y); x[4] = bflo(a.z); x[5] = bfhi(a.z); x[6] = bflo(a.w); x[7] = bfhi(a.w);
;     x[8] = bflo(b.x); x[9] = bfhi(b.x); x[10] = bflo(b.y); x[11] = bfhi(b.y); x[12] = bflo(b.z); x[13] = bfhi(b.z); x[14] = bflo(b.w); x[15] = bfhi(b.w);
; }
; __device__ __forceinline__ void qk_prep_store(u32x4 a, u32x4 b, const float* gain, int sub, int pos, float scale, bf16_t* dst, int lane) {
;     float x[16]; unpack16(a, b, x);
;     float ss = 0.f;
; #pragma unroll
;     for (int i = 0; i < 16; ++i) ss += x[i] * x[i];
;     ss += shx(ss, 1, lane); ss += shx(ss, 2, lane);
;     const float r = rsqrtf(ss * (1.0f / 64.0f) + EPS);
; #pragma unroll
;     for (int i = 0; i < 16; ++i) x[i] = x[i] * r * gain[sub * 16 + i];
.LBB0_827:
	global_load_dwordx4 v[42:45], v[68:69], off
	global_load_dwordx4 v[46:49], v[68:69], off offset:16
	global_load_dwordx4 v[60:63], v[68:69], off offset:32
	global_load_dwordx4 v[74:77], v[68:69], off offset:48
	s_waitcnt vmcnt(6)
	v_lshlrev_b32_e32 v78, 16, v54
	v_and_b32_e32 v79, 0xffff0000, v54
	v_lshlrev_b32_e32 v54, 16, v55
	v_and_b32_e32 v55, 0xffff0000, v55
	v_pk_mul_f32 v[88:89], v[78:79], v[78:79]
	v_pk_mul_f32 v[92:93], v[54:55], v[54:55]
	v_add_f32_e32 v59, v88, v89
	v_lshlrev_b32_e32 v82, 16, v56
	v_and_b32_e32 v83, 0xffff0000, v56
	v_add_f32_e32 v59, v92, v59
	v_pk_mul_f32 v[160:161], v[82:83], v[82:83]
	v_add_f32_e32 v59, v93, v59
	v_add_f32_e32 v59, v160, v59
	v_lshlrev_b32_e32 v87, 16, v57
	v_add_f32_e32 v59, v161, v59
	v_and_b32_e32 v58, 0xffff0000, v57
	v_lshlrev_b32_e32 v80, 16, v50
	v_and_b32_e32 v81, 0xffff0000, v50
	v_fmac_f32_e32 v59, v87, v87
	v_pk_mul_f32 v[90:91], v[80:81], v[80:81]
	v_fmac_f32_e32 v59, v58, v58
	v_lshlrev_b32_e32 v50, 16, v51
	v_and_b32_e32 v51, 0xffff0000, v51
	v_add_f32_e32 v59, v90, v59
	v_pk_mul_f32 v[158:159], v[50:51], v[50:51]
	v_add_f32_e32 v59, v91, v59
	v_lshlrev_b32_e32 v56, 16, v52
	v_and_b32_e32 v57, 0xffff0000, v52
	v_add_f32_e32 v59, v158, v59
	v_pk_mul_f32 v[162:163], v[56:57], v[56:57]
	v_add_f32_e32 v59, v159, v59
	v_and_b32_e32 v64, 0xffff0000, v53
	v_lshlrev_b32_e32 v65, 16, v53
	v_add_f32_e32 v59, v162, v59
	v_pk_mul_f32 v[52:53], v[64:65], v[64:65]
	v_add_f32_e32 v59, v163, v59
	v_add_f32_e32 v53, v53, v59
	v_add_f32_e32 v52, v52, v53
	s_nop 1
	v_mov_b32_dpp v53, v52 quad_perm:[1,0,3,2] row_mask:0xf bank_mask:0xf
	s_mov_b32 s2, 0x800000
	v_mov_b32_e32 v59, v64
	s_waitcnt lgkmcnt(0)
	v_add_f32_e32 v52, v52, v53
	s_nop 1
	v_mov_b32_dpp v53, v52 quad_perm:[2,3,0,1] row_mask:0xf bank_mask:0xf
	s_waitcnt lgkmcnt(0)
	v_add_f32_e32 v52, v52, v53
	v_fmamk_f32 v52, v52, 0x3c800000, v205
	v_mul_f32_e32 v53, 0x4b800000, v52
	v_cmp_gt_f32_e32 vcc, s2, v52
	s_nop 1
	v_cndmask_b32_e32 v52, v52, v53, vcc
	v_rsq_f32_e32 v52, v52
	s_nop 0
	v_mul_f32_e32 v53, 0x45800000, v52
	v_cndmask_b32_e32 v52, v52, v53, vcc
	v_mul_f32_e32 v64, v52, v87
	v_pk_mul_f32 v[88:89], v[52:53], v[50:51] op_sel_hi:[0,1]
	v_mul_f32_e32 v51, v52, v65
	v_pk_mul_f32 v[78:79], v[52:53], v[78:79] op_sel_hi:[0,1]
	v_pk_mul_f32 v[54:55], v[52:53], v[54:55] op_sel_hi:[0,1]
	v_pk_mul_f32 v[82:83], v[52:53], v[82:83] op_sel_hi:[0,1]
	v_pk_mul_f32 v[80:81], v[52:53], v[80:81] op_sel_hi:[0,1]
	v_pk_mul_f32 v[90:91], v[52:53], v[56:57] op_sel_hi:[0,1]
	v_pk_mul_f32 v[52:53], v[52:53], v[58:59] op_sel_hi:[0,1]
	s_waitcnt vmcnt(3)
	v_pk_mul_f32 v[58:59], v[42:43], v[78:79]
	s_waitcnt vmcnt(2)
	v_mul_f32_e32 v50, v48, v64
	v_pk_mul_f32 v[56:57], v[44:45], v[54:55]
	s_waitcnt vmcnt(0)
	v_mul_f32_e32 v48, v51, v76
	v_mov_b32_e32 v76, v49
	v_pk_mul_f32 v[54:55], v[46:47], v[82:83]
	v_pk_mul_f32 v[46:47], v[60:61], v[80:81]
	v_pk_mul_f32 v[44:45], v[88:89], v[62:63]
	v_pk_mul_f32 v[42:43], v[90:91], v[74:75]
	v_pk_mul_f32 v[52:53], v[76:77], v[52:53]
	s_and_saveexec_b64 s[2:3], s[4:5]
	s_cbranch_execz .LBB0_829
; __device__ __forceinline__ float2 twid(float turns) { return make_float2(__builtin_amdgcn_cosf(turns), __builtin_amdgcn_sinf(turns)); }
; __device__ __forceinline__ void qk_prep_store(u32x4 a, u32x4 b, const float* gain, int sub, int pos, float scale, bf16_t* dst, int lane) {
;     ...
;     if (sub == 0) {
;         const float ihi[8] = {(float)(1.0 / 3.14159265358979323846), (float)(0.19392274474868576 / 3.14159265358979323846), (float)(0.03760603093086393 / 3.14159265358979323846), (float)(0.007292664737217109 / 3.14159265358979323846),
;                               (float)(0.001414213562373095 / 3.14159265358979323846), (float)(0.0002742481756762073 / 3.14159265358979323846), (float)(5.318295896944988e-05 / 3.14159265358979323846), (float)(1.031338537721246e-05 / 3.14159265358979323846)};
;         const float ilo[8] = {(float)(1.0 / 3.14159265358979323846 - (double)(float)(1.0 / 3.14159265358979323846)), (float)(0.19392274474868576 / 3.14159265358979323846 - (double)(float)(0.19392274474868576 / 3.14159265358979323846)),
;                               (float)(0.03760603093086393 / 3.14159265358979323846 - (double)(float)(0.03760603093086393 / 3.14159265358979323846)), (float)(0.007292664737217109 / 3.14159265358979323846 - (double)(float)(0.007292664737217109 / 3.14159265358979323846)),
;                               (float)(0.001414213562373095 / 3.14159265358979323846 - (double)(float)(0.001414213562373095 / 3.14159265358979323846)), (float)(0.0002742481756762073 / 3.14159265358979323846 - (double)(float)(0.0002742481756762073 / 3.14159265358979323846)),
;                               (float)(5.318295896944988e-05 / 3.14159265358979323846 - (double)(float)(5.318295896944988e-05 / 3.14159265358979323846)), (float)(1.031338537721246e-05 / 3.14159265358979323846 - (double)(float)(1.031338537721246e-05 / 3.14159265358979323846))};
; #pragma unroll
;         for (int j = 0; j < 8; ++j) {
;             const float fp = (float)pos, ph = fp * ihi[j], pe = __builtin_fmaf(fp, ihi[j], -ph) + fp * ilo[j];
;             const float red = (ph - 2.0f * rintf(0.5f * ph)) + pe;
;             const float2 cs = twid(0.5f * red); const float c = cs.x, s = cs.y;
;             const float x1 = x[j], x2 = x[8 + j];
;             x[j] = x1 * c - x2 * s; x[8 + j] = x2 * c + x1 * s;
;         }
;     }
	v_cvt_f32_i32_e32 v60, v86
	s_mov_b32 s16, 0x3ea2f983
	s_mov_b32 s15, 0x3d7cd601
	v_readlane_b32 s36, v254, 14
	v_mul_f32_e32 v49, 0x3ea2f983, v60
	v_mul_f32_e32 v61, 0.5, v49
	v_fma_f32 v51, v60, s16, -v49
	v_rndne_f32_e32 v61, v61
	v_fmac_f32_e32 v51, 0x325c9c88, v60
	v_fmac_f32_e32 v49, -2.0, v61
	v_add_f32_e32 v49, v51, v49
	v_mul_f32_e32 v49, 0.5, v49
	v_mul_f32_e32 v75, 0x3d7cd601, v60
	v_cos_f32_e32 v62, v49
	v_sin_f32_e32 v64, v49
	v_mul_f32_e32 v49, 0.5, v75
	s_mov_b32 s16, 0xb045cd43
	v_fma_f32 v74, v60, s15, -v75
	v_rndne_f32_e32 v61, v49
	s_mov_b32 s17, -2.0
	v_pk_fma_f32 v[74:75], v[60:61], s[16:17], v[74:75]
	s_mov_b32 s15, 0x3c441f60
	v_add_f32_e32 v49, v74, v75
	v_mul_f32_e32 v49, 0.5, v49
	v_sin_f32_e32 v65, v49
	v_cos_f32_e32 v63, v49
	v_mul_f32_e32 v49, 0x3c441f60, v60
	v_fma_f32 v51, v60, s15, -v49
	v_pk_mul_f32 v[74:75], v[64:65], v[46:47]
	v_fmac_f32_e32 v51, 0x2fe5870b, v60
	v_pk_fma_f32 v[74:75], v[62:63], v[58:59], v[74:75] neg_lo:[0,0,1] neg_hi:[0,0,1]
	v_pk_mul_f32 v[58:59], v[64:65], v[58:59]
	v_mul_f32_e32 v65, 0x3b182169, v60
	v_pk_fma_f32 v[46:47], v[62:63], v[46:47], v[58:59]
	v_mul_f32_e32 v58, 0.5, v49
	v_rndne_f32_e32 v58, v58
	v_fmac_f32_e32 v49, -2.0, v58
	v_add_f32_e32 v49, v51, v49
	v_mul_f32_e32 v49, 0.5, v49
	v_cos_f32_e32 v58, v49
	v_sin_f32_e32 v62, v49
	s_mov_b32 s15, 0x3b182169
	v_mul_f32_e32 v49, 0.5, v65
	v_readlane_b32 s37, v254, 15
	v_fma_f32 v64, v60, s15, -v65
	v_rndne_f32_e32 v61, v49
	s_mov_b32 s37, s17
	v_pk_fma_f32 v[64:65], v[60:61], s[36:37], v[64:65]
	s_mov_b32 s16, s36
	v_add_f32_e32 v49, v64, v65
	v_mul_f32_e32 v49, 0.5, v49
	v_cos_f32_e32 v59, v49
	v_sin_f32_e32 v63, v49
	v_writelane_b32 v254, s16, 14
	s_mov_b32 s15, 0x39ec0335
	v_pk_mul_f32 v[64:65], v[62:63], v[44:45]
	v_writelane_b32 v254, s17, 15
	v_pk_mul_f32 v[44:45], v[58:59], v[44:45]
	v_pk_fma_f32 v[64:65], v[58:59], v[56:57], v[64:65] neg_lo:[0,0,1] neg_hi:[0,0,1]
	v_pk_fma_f32 v[44:45], v[62:63], v[56:57], v[44:45]
	v_mul_f32_e32 v57, 0x39ec0335, v60
	v_readlane_b32 s36, v254, 16
	v_mul_f32_e32 v49, 0.5, v57
	v_readlane_b32 s37, v254, 17
	v_fma_f32 v56, v60, s15, -v57
	v_rndne_f32_e32 v61, v49
	s_mov_b32 s37, s17
	s_mov_b32 s16, s36
	v_pk_fma_f32 v[56:57], v[60:61], s[36:37], v[56:57]
	v_writelane_b32 v254, s16, 16
	v_add_f32_e32 v49, v56, v57
	v_mul_f32_e32 v49, 0.5, v49
	v_writelane_b32 v254, s17, 17
	v_mul_f32_e32 v63, 0x38b712a2, v60
	v_cos_f32_e32 v56, v49
	v_sin_f32_e32 v58, v49
	s_mov_b32 s15, 0x38b712a2
	v_mul_f32_e32 v49, 0.5, v63
	v_readlane_b32 s36, v254, 18
	v_fma_f32 v62, v60, s15, -v63
	v_rndne_f32_e32 v61, v49
	s_mov_b32 s16, s36
	v_pk_fma_f32 v[62:63], v[60:61], s[16:17], v[62:63]
	s_mov_b32 s15, 0x378e0206
	v_add_f32_e32 v49, v62, v63
	v_mul_f32_e32 v49, 0.5, v49
	v_cos_f32_e32 v57, v49
	v_sin_f32_e32 v59, v49
	v_mul_f32_e32 v49, 0x378e0206, v60
	v_fma_f32 v51, v60, s15, -v49
	v_fmac_f32_e32 v51, 0x2a947bf1, v60
	v_pk_mul_f32 v[62:63], v[58:59], v[42:43]
	v_pk_mul_f32 v[42:43], v[56:57], v[42:43]
	v_pk_fma_f32 v[62:63], v[56:57], v[54:55], v[62:63] neg_lo:[0,0,1] neg_hi:[0,0,1]
	v_pk_fma_f32 v[42:43], v[58:59], v[54:55], v[42:43]
	v_mul_f32_e32 v54, 0.5, v49
	v_rndne_f32_e32 v54, v54
	v_fmac_f32_e32 v49, -2.0, v54
	v_add_f32_e32 v49, v51, v49
	v_mul_f32_e32 v49, 0.5, v49
	v_cos_f32_e32 v54, v49
	v_sin_f32_e32 v56, v49
	v_mul_f32_e32 v49, 0x365c4efa, v60
	s_mov_b32 s15, 0x365c4efa
	v_mul_f32_e32 v55, 0.5, v49
	v_fma_f32 v51, v60, s15, -v49
	v_rndne_f32_e32 v55, v55
	v_fmac_f32_e32 v51, 0x28c5eb61, v60
	v_fmac_f32_e32 v49, -2.0, v55
	v_add_f32_e32 v49, v51, v49
	v_mul_f32_e32 v49, 0.5, v49
	v_sin_f32_e32 v57, v49
	v_cos_f32_e32 v55, v49
	v_mov_b32_e32 v49, v53
	v_mul_f32_e32 v58, v54, v48
	v_mov_b32_e32 v51, v52
	v_pk_mul_f32 v[48:49], v[56:57], v[48:49]
	v_mul_f32_e32 v76, v56, v50
	v_pk_fma_f32 v[50:51], v[54:55], v[50:51], v[48:49] neg_lo:[0,0,1] neg_hi:[0,0,1]
	v_mov_b32_e32 v54, v57
	v_pk_mul_f32 v[48:49], v[54:55], v[52:53]
	v_readlane_b32 s37, v254, 19
	v_mov_b32_e32 v77, v48
	v_mov_b32_e32 v59, v49
	v_writelane_b32 v254, s36, 18
	v_pk_add_f32 v[48:49], v[76:77], v[58:59]
	v_mov_b32_e32 v58, v74
	v_writelane_b32 v254, s37, 19
	v_mov_b32_e32 v59, v75
	v_mov_b32_e32 v56, v64
	v_mov_b32_e32 v57, v65
	v_mov_b32_e32 v54, v62
	v_mov_b32_e32 v55, v63
	v_mov_b32_e32 v52, v51
	v_mov_b32_e32 v53, v49

; __device__ __forceinline__ float bflo(unsigned u) { return __uint_as_float(u << 16); }
; __device__ __forceinline__ float bfhi(unsigned u) { return __uint_as_float(u & 0xffff0000u); }
; __device__ __forceinline__ float shx(float v, int mask, int lane) { return __int_as_float(__builtin_amdgcn_ds_bpermute((lane ^ mask) << 2, __float_as_int(v))); }
; __device__ __forceinline__ void unpack16(const u32x4& a, const u32x4& b, float (&x)[16]) {
;     x[0] = bflo(a.x); x[1] = bfhi(a.x); x[2] = bflo(a.y); x[3] = bfhi(a.y); x[4] = bflo(a.z); x[5] = bfhi(a.z); x[6] = bflo(a.w); x[7] = bfhi(a.w);
;     x[8] = bflo(b.x); x[9] = bfhi(b.x); x[10] = bflo(b.y); x[11] = bfhi(b.y); x[12] = bflo(b.z); x[13] = bfhi(b.z); x[14] = bflo(b.w); x[15] = bfhi(b.w);
; }
; __device__ __forceinline__ void qk_prep_store(u32x4 a, u32x4 b, const float* gain, int sub, int pos, float scale, bf16_t* dst, int lane) {
;     float x[16]; unpack16(a, b, x);
;     float ss = 0.f;
; #pragma unroll
;     for (int i = 0; i < 16; ++i) ss += x[i] * x[i];
;     ss += shx(ss, 1, lane); ss += shx(ss, 2, lane);
;     const float r = rsqrtf(ss * (1.0f / 64.0f) + EPS);
; #pragma unroll
;     for (int i = 0; i < 16; ++i) x[i] = x[i] * r * gain[sub * 16 + i];
.LBB0_830:
	global_load_dwordx4 v[30:33], v[68:69], off
	global_load_dwordx4 v[34:37], v[68:69], off offset:16
	global_load_dwordx4 v[44:47], v[68:69], off offset:32
	global_load_dwordx4 v[48:51], v[68:69], off offset:48
	s_waitcnt vmcnt(6)
	v_lshlrev_b32_e32 v54, 16, v38
	v_and_b32_e32 v55, 0xffff0000, v38
	v_lshlrev_b32_e32 v38, 16, v39
	v_and_b32_e32 v39, 0xffff0000, v39
	v_pk_mul_f32 v[60:61], v[54:55], v[54:55]
	v_pk_mul_f32 v[64:65], v[38:39], v[38:39]
	s_waitcnt vmcnt(4)
	v_add_f32_e32 v43, v60, v61
	v_lshlrev_b32_e32 v58, 16, v40
	v_and_b32_e32 v59, 0xffff0000, v40
	v_add_f32_e32 v43, v64, v43
	v_pk_mul_f32 v[76:77], v[58:59], v[58:59]
	v_add_f32_e32 v43, v65, v43
	v_add_f32_e32 v43, v76, v43
	v_lshlrev_b32_e32 v80, 16, v41
	v_add_f32_e32 v43, v77, v43
	v_and_b32_e32 v42, 0xffff0000, v41
	v_lshlrev_b32_e32 v56, 16, v26
	v_and_b32_e32 v57, 0xffff0000, v26
	v_fmac_f32_e32 v43, v80, v80
	v_pk_mul_f32 v[62:63], v[56:57], v[56:57]
	v_fmac_f32_e32 v43, v42, v42
	v_lshlrev_b32_e32 v26, 16, v27
	v_and_b32_e32 v27, 0xffff0000, v27
	v_add_f32_e32 v43, v62, v43
	v_pk_mul_f32 v[74:75], v[26:27], v[26:27]
	v_add_f32_e32 v43, v63, v43
	v_lshlrev_b32_e32 v40, 16, v28
	v_and_b32_e32 v41, 0xffff0000, v28
	v_add_f32_e32 v43, v74, v43
	v_pk_mul_f32 v[78:79], v[40:41], v[40:41]
	v_add_f32_e32 v43, v75, v43
	v_and_b32_e32 v52, 0xffff0000, v29
	v_lshlrev_b32_e32 v53, 16, v29
	v_add_f32_e32 v43, v78, v43
	v_pk_mul_f32 v[28:29], v[52:53], v[52:53]
	v_add_f32_e32 v43, v79, v43
	v_add_f32_e32 v29, v29, v43
	v_add_f32_e32 v28, v28, v29
	s_nop 1
	v_mov_b32_dpp v29, v28 quad_perm:[1,0,3,2] row_mask:0xf bank_mask:0xf
	s_mov_b32 s2, 0x800000
	v_mov_b32_e32 v43, v52
	s_waitcnt lgkmcnt(0)
	v_add_f32_e32 v28, v28, v29
	s_nop 1
	v_mov_b32_dpp v29, v28 quad_perm:[2,3,0,1] row_mask:0xf bank_mask:0xf
	s_waitcnt lgkmcnt(0)
	v_add_f32_e32 v28, v28, v29
	v_fmamk_f32 v28, v28, 0x3c800000, v205
	v_mul_f32_e32 v29, 0x4b800000, v28
	v_cmp_gt_f32_e32 vcc, s2, v28
	s_nop 1
	v_cndmask_b32_e32 v28, v28, v29, vcc
	v_rsq_f32_e32 v28, v28
	s_nop 0
	v_mul_f32_e32 v29, 0x45800000, v28
	v_cndmask_b32_e32 v28, v28, v29, vcc
	v_pk_mul_f32 v[54:55], v[28:29], v[54:55] op_sel_hi:[0,1]
	v_pk_mul_f32 v[38:39], v[28:29], v[38:39] op_sel_hi:[0,1]
	v_pk_mul_f32 v[58:59], v[28:29], v[58:59] op_sel_hi:[0,1]
	v_mul_f32_e32 v29, v28, v80
	v_mul_f32_e32 v62, v28, v53
	v_pk_mul_f32 v[56:57], v[28:29], v[56:57] op_sel_hi:[0,1]
	v_pk_mul_f32 v[26:27], v[28:29], v[26:27] op_sel_hi:[0,1]
	v_pk_mul_f32 v[60:61], v[28:29], v[40:41] op_sel_hi:[0,1]
	v_pk_mul_f32 v[52:53], v[28:29], v[42:43] op_sel_hi:[0,1]
	s_waitcnt vmcnt(3)
	v_pk_mul_f32 v[40:41], v[32:33], v[38:39]
	v_pk_mul_f32 v[42:43], v[30:31], v[54:55]
	s_waitcnt vmcnt(2)
	v_pk_mul_f32 v[38:39], v[34:35], v[58:59]
	s_waitcnt vmcnt(0)
	v_mul_f32_e32 v32, v62, v50
	v_mov_b32_e32 v50, v37
	v_mul_f32_e32 v34, v36, v29
	v_pk_mul_f32 v[30:31], v[44:45], v[56:57]
	v_pk_mul_f32 v[28:29], v[26:27], v[46:47]
	v_pk_mul_f32 v[26:27], v[60:61], v[48:49]
	v_pk_mul_f32 v[36:37], v[50:51], v[52:53]
	s_and_saveexec_b64 s[2:3], s[4:5]
	s_cbranch_execz .LBB0_832
; __device__ __forceinline__ float2 twid(float turns) { return make_float2(__builtin_amdgcn_cosf(turns), __builtin_amdgcn_sinf(turns)); }
; __device__ __forceinline__ void qk_prep_store(u32x4 a, u32x4 b, const float* gain, int sub, int pos, float scale, bf16_t* dst, int lane) {
;     ...
;     if (sub == 0) {
;         const float ihi[8] = {(float)(1.0 / 3.14159265358979323846), (float)(0.19392274474868576 / 3.14159265358979323846), (float)(0.03760603093086393 / 3.14159265358979323846), (float)(0.007292664737217109 / 3.14159265358979323846),
;                               (float)(0.001414213562373095 / 3.14159265358979323846), (float)(0.0002742481756762073 / 3.14159265358979323846), (float)(5.318295896944988e-05 / 3.14159265358979323846), (float)(1.031338537721246e-05 / 3.14159265358979323846)};
;         const float ilo[8] = {(float)(1.0 / 3.14159265358979323846 - (double)(float)(1.0 / 3.14159265358979323846)), (float)(0.19392274474868576 / 3.14159265358979323846 - (double)(float)(0.19392274474868576 / 3.14159265358979323846)),
;                               (float)(0.03760603093086393 / 3.14159265358979323846 - (double)(float)(0.03760603093086393 / 3.14159265358979323846)), (float)(0.007292664737217109 / 3.14159265358979323846 - (double)(float)(0.007292664737217109 / 3.14159265358979323846)),
;                               (float)(0.001414213562373095 / 3.14159265358979323846 - (double)(float)(0.001414213562373095 / 3.14159265358979323846)), (float)(0.0002742481756762073 / 3.14159265358979323846 - (double)(float)(0.0002742481756762073 / 3.14159265358979323846)),
;                               (float)(5.318295896944988e-05 / 3.14159265358979323846 - (double)(float)(5.318295896944988e-05 / 3.14159265358979323846)), (float)(1.031338537721246e-05 / 3.14159265358979323846 - (double)(float)(1.031338537721246e-05 / 3.14159265358979323846))};
; #pragma unroll
;         for (int j = 0; j < 8; ++j) {
;             const float fp = (float)pos, ph = fp * ihi[j], pe = __builtin_fmaf(fp, ihi[j], -ph) + fp * ilo[j];
;             const float red = (ph - 2.0f * rintf(0.5f * ph)) + pe;
;             const float2 cs = twid(0.5f * red); const float c = cs.x, s = cs.y;
;             const float x1 = x[j], x2 = x[8 + j];
;             x[j] = x1 * c - x2 * s; x[8 + j] = x2 * c + x1 * s;
;         }
;     }
	v_cvt_f32_i32_e32 v44, v85
	s_mov_b32 s16, 0x3ea2f983
	s_mov_b32 s15, 0x3d7cd601
	v_readlane_b32 s36, v254, 14
	v_mul_f32_e32 v33, 0x3ea2f983, v44
	v_mul_f32_e32 v45, 0.5, v33
	v_fma_f32 v35, v44, s16, -v33
	v_rndne_f32_e32 v45, v45
	v_fmac_f32_e32 v35, 0x325c9c88, v44
	v_fmac_f32_e32 v33, -2.0, v45
	v_add_f32_e32 v33, v35, v33
	v_mul_f32_e32 v33, 0.5, v33
	v_mul_f32_e32 v51, 0x3d7cd601, v44
	v_cos_f32_e32 v46, v33
	v_sin_f32_e32 v48, v33
	v_mul_f32_e32 v33, 0.5, v51
	s_mov_b32 s16, 0xb045cd43
	v_fma_f32 v50, v44, s15, -v51
	v_rndne_f32_e32 v45, v33
	s_mov_b32 s17, -2.0
	v_pk_fma_f32 v[50:51], v[44:45], s[16:17], v[50:51]
	s_mov_b32 s15, 0x3c441f60
	v_add_f32_e32 v33, v50, v51
	v_mul_f32_e32 v33, 0.5, v33
	v_sin_f32_e32 v49, v33
	v_cos_f32_e32 v47, v33
	v_mul_f32_e32 v33, 0x3c441f60, v44
	v_fma_f32 v35, v44, s15, -v33
	v_pk_mul_f32 v[50:51], v[48:49], v[30:31]
	v_fmac_f32_e32 v35, 0x2fe5870b, v44
	v_pk_fma_f32 v[50:51], v[46:47], v[42:43], v[50:51] neg_lo:[0,0,1] neg_hi:[0,0,1]
	v_pk_mul_f32 v[42:43], v[48:49], v[42:43]
	v_mul_f32_e32 v49, 0x3b182169, v44
	v_pk_fma_f32 v[30:31], v[46:47], v[30:31], v[42:43]
	v_mul_f32_e32 v42, 0.5, v33
	v_rndne_f32_e32 v42, v42
	v_fmac_f32_e32 v33, -2.0, v42
	v_add_f32_e32 v33, v35, v33
	v_mul_f32_e32 v33, 0.5, v33
	v_cos_f32_e32 v42, v33
	v_sin_f32_e32 v46, v33
	s_mov_b32 s15, 0x3b182169
	v_mul_f32_e32 v33, 0.5, v49
	v_readlane_b32 s37, v254, 15
	v_fma_f32 v48, v44, s15, -v49
	v_rndne_f32_e32 v45, v33
	s_mov_b32 s37, s17
	v_pk_fma_f32 v[48:49], v[44:45], s[36:37], v[48:49]
	s_mov_b32 s16, s36
	v_add_f32_e32 v33, v48, v49
	v_mul_f32_e32 v33, 0.5, v33
	v_cos_f32_e32 v43, v33
	v_sin_f32_e32 v47, v33
	v_writelane_b32 v254, s16, 14
	s_mov_b32 s15, 0x39ec0335
	v_pk_mul_f32 v[48:49], v[46:47], v[28:29]
	v_writelane_b32 v254, s17, 15
	v_pk_mul_f32 v[28:29], v[42:43], v[28:29]
	v_pk_fma_f32 v[48:49], v[42:43], v[40:41], v[48:49] neg_lo:[0,0,1] neg_hi:[0,0,1]
	v_pk_fma_f32 v[28:29], v[46:47], v[40:41], v[28:29]
	v_mul_f32_e32 v41, 0x39ec0335, v44
	v_readlane_b32 s36, v254, 16
	v_mul_f32_e32 v33, 0.5, v41
	v_readlane_b32 s37, v254, 17
	v_fma_f32 v40, v44, s15, -v41
	v_rndne_f32_e32 v45, v33
	s_mov_b32 s37, s17
	s_mov_b32 s16, s36
	v_pk_fma_f32 v[40:41], v[44:45], s[36:37], v[40:41]
	v_writelane_b32 v254, s16, 16
	v_add_f32_e32 v33, v40, v41
	v_mul_f32_e32 v33, 0.5, v33
	v_writelane_b32 v254, s17, 17
	v_mul_f32_e32 v47, 0x38b712a2, v44
	v_cos_f32_e32 v40, v33
	v_sin_f32_e32 v42, v33
	s_mov_b32 s15, 0x38b712a2
	v_mul_f32_e32 v33, 0.5, v47
	v_readlane_b32 s36, v254, 18
	v_fma_f32 v46, v44, s15, -v47
	v_rndne_f32_e32 v45, v33
	s_mov_b32 s16, s36
	v_pk_fma_f32 v[46:47], v[44:45], s[16:17], v[46:47]
	s_mov_b32 s15, 0x378e0206
	v_add_f32_e32 v33, v46, v47
	v_mul_f32_e32 v33, 0.5, v33
	v_cos_f32_e32 v41, v33
	v_sin_f32_e32 v43, v33
	v_mul_f32_e32 v33, 0x378e0206, v44
	v_fma_f32 v35, v44, s15, -v33
	v_fmac_f32_e32 v35, 0x2a947bf1, v44
	v_pk_mul_f32 v[46:47], v[42:43], v[26:27]
	v_pk_mul_f32 v[26:27], v[40:41], v[26:27]
	v_pk_fma_f32 v[46:47], v[40:41], v[38:39], v[46:47] neg_lo:[0,0,1] neg_hi:[0,0,1]
	v_pk_fma_f32 v[26:27], v[42:43], v[38:39], v[26:27]
	v_mul_f32_e32 v38, 0.5, v33
	v_rndne_f32_e32 v38, v38
	v_fmac_f32_e32 v33, -2.0, v38
	v_add_f32_e32 v33, v35, v33
	v_mul_f32_e32 v33, 0.5, v33
	v_cos_f32_e32 v38, v33
	v_sin_f32_e32 v40, v33
	v_mul_f32_e32 v33, 0x365c4efa, v44
	s_mov_b32 s15, 0x365c4efa
	v_mul_f32_e32 v39, 0.5, v33
	v_fma_f32 v35, v44, s15, -v33
	v_rndne_f32_e32 v39, v39
	v_fmac_f32_e32 v35, 0x28c5eb61, v44
	v_fmac_f32_e32 v33, -2.0, v39
	v_add_f32_e32 v33, v35, v33
	v_mul_f32_e32 v33, 0.5, v33
	v_sin_f32_e32 v41, v33
	v_cos_f32_e32 v39, v33
	v_mov_b32_e32 v33, v37
	v_mul_f32_e32 v42, v38, v32
	v_mov_b32_e32 v35, v36
	v_pk_mul_f32 v[32:33], v[40:41], v[32:33]
	v_mul_f32_e32 v52, v40, v34
	v_pk_fma_f32 v[34:35], v[38:39], v[34:35], v[32:33] neg_lo:[0,0,1] neg_hi:[0,0,1]
	v_mov_b32_e32 v38, v41
	v_pk_mul_f32 v[32:33], v[38:39], v[36:37]
	v_readlane_b32 s37, v254, 19
	v_mov_b32_e32 v53, v32
	v_mov_b32_e32 v43, v33
	v_writelane_b32 v254, s36, 18
	v_pk_add_f32 v[32:33], v[52:53], v[42:43]
	v_mov_b32_e32 v42, v50
	v_writelane_b32 v254, s37, 19
	v_mov_b32_e32 v43, v51
	v_mov_b32_e32 v40, v48
	v_mov_b32_e32 v41, v49
	v_mov_b32_e32 v38, v46
	v_mov_b32_e32 v39, v47
	v_mov_b32_e32 v36, v35
	v_mov_b32_e32 v37, v33

; __device__ __forceinline__ float bflo(unsigned u) { return __uint_as_float(u << 16); }
; __device__ __forceinline__ float bfhi(unsigned u) { return __uint_as_float(u & 0xffff0000u); }
; __device__ __forceinline__ float shx(float v, int mask, int lane) { return __int_as_float(__builtin_amdgcn_ds_bpermute((lane ^ mask) << 2, __float_as_int(v))); }
; __device__ __forceinline__ void unpack16(const u32x4& a, const u32x4& b, float (&x)[16]) {
;     x[0] = bflo(a.x); x[1] = bfhi(a.x); x[2] = bflo(a.y); x[3] = bfhi(a.y); x[4] = bflo(a.z); x[5] = bfhi(a.z); x[6] = bflo(a.w); x[7] = bfhi(a.w);
;     x[8] = bflo(b.x); x[9] = bfhi(b.x); x[10] = bflo(b.y); x[11] = bfhi(b.y); x[12] = bflo(b.z); x[13] = bfhi(b.z); x[14] = bflo(b.w); x[15] = bfhi(b.w);
; }
; __device__ __forceinline__ void qk_prep_store(u32x4 a, u32x4 b, const float* gain, int sub, int pos, float scale, bf16_t* dst, int lane) {
;     float x[16]; unpack16(a, b, x);
;     float ss = 0.f;
; #pragma unroll
;     for (int i = 0; i < 16; ++i) ss += x[i] * x[i];
;     ss += shx(ss, 1, lane); ss += shx(ss, 2, lane);
;     const float r = rsqrtf(ss * (1.0f / 64.0f) + EPS);
; #pragma unroll
;     for (int i = 0; i < 16; ++i) x[i] = x[i] * r * gain[sub * 16 + i];
.LBB0_833:
	global_load_dwordx4 v[10:13], v[68:69], off
	global_load_dwordx4 v[14:17], v[68:69], off offset:16
	global_load_dwordx4 v[28:31], v[68:69], off offset:32
	global_load_dwordx4 v[32:35], v[68:69], off offset:48
	s_waitcnt vmcnt(6)
	v_lshlrev_b32_e32 v38, 16, v22
	v_and_b32_e32 v39, 0xffff0000, v22
	v_lshlrev_b32_e32 v22, 16, v23
	v_and_b32_e32 v23, 0xffff0000, v23
	s_waitcnt vmcnt(4)
	v_pk_mul_f32 v[44:45], v[38:39], v[38:39]
	v_pk_mul_f32 v[48:49], v[22:23], v[22:23]
	v_add_f32_e32 v27, v44, v45
	v_lshlrev_b32_e32 v42, 16, v24
	v_and_b32_e32 v43, 0xffff0000, v24
	v_add_f32_e32 v27, v48, v27
	v_pk_mul_f32 v[52:53], v[42:43], v[42:43]
	v_add_f32_e32 v27, v49, v27
	v_add_f32_e32 v27, v52, v27
	v_lshlrev_b32_e32 v56, 16, v25
	v_add_f32_e32 v27, v53, v27
	v_and_b32_e32 v26, 0xffff0000, v25
	v_lshlrev_b32_e32 v40, 16, v18
	v_and_b32_e32 v41, 0xffff0000, v18
	v_fmac_f32_e32 v27, v56, v56
	v_pk_mul_f32 v[46:47], v[40:41], v[40:41]
	v_fmac_f32_e32 v27, v26, v26
	v_lshlrev_b32_e32 v18, 16, v19
	v_and_b32_e32 v19, 0xffff0000, v19
	v_add_f32_e32 v27, v46, v27
	v_pk_mul_f32 v[50:51], v[18:19], v[18:19]
	v_add_f32_e32 v27, v47, v27
	v_lshlrev_b32_e32 v24, 16, v20
	v_and_b32_e32 v25, 0xffff0000, v20
	v_add_f32_e32 v27, v50, v27
	v_pk_mul_f32 v[54:55], v[24:25], v[24:25]
	v_add_f32_e32 v27, v51, v27
	v_and_b32_e32 v36, 0xffff0000, v21
	v_lshlrev_b32_e32 v37, 16, v21
	v_add_f32_e32 v27, v54, v27
	v_pk_mul_f32 v[20:21], v[36:37], v[36:37]
	v_add_f32_e32 v27, v55, v27
	v_add_f32_e32 v21, v21, v27
	v_add_f32_e32 v20, v20, v21
	s_nop 1
	v_mov_b32_dpp v21, v20 quad_perm:[1,0,3,2] row_mask:0xf bank_mask:0xf
	s_mov_b32 s2, 0x800000
	v_mov_b32_e32 v27, v36
	s_waitcnt lgkmcnt(0)
	v_add_f32_e32 v20, v20, v21
	s_nop 1
	v_mov_b32_dpp v21, v20 quad_perm:[2,3,0,1] row_mask:0xf bank_mask:0xf
	s_waitcnt lgkmcnt(0)
	v_add_f32_e32 v20, v20, v21
	v_fmamk_f32 v20, v20, 0x3c800000, v205
	v_mul_f32_e32 v21, 0x4b800000, v20
	v_cmp_gt_f32_e32 vcc, s2, v20
	s_nop 1
	v_cndmask_b32_e32 v20, v20, v21, vcc
	v_rsq_f32_e32 v20, v20
	s_nop 0
	v_mul_f32_e32 v21, 0x45800000, v20
	v_cndmask_b32_e32 v20, v20, v21, vcc
	v_mul_f32_e32 v36, v20, v56
	v_pk_mul_f32 v[44:45], v[20:21], v[18:19] op_sel_hi:[0,1]
	v_mul_f32_e32 v19, v20, v37
	v_pk_mul_f32 v[38:39], v[20:21], v[38:39] op_sel_hi:[0,1]
	v_pk_mul_f32 v[22:23], v[20:21], v[22:23] op_sel_hi:[0,1]
	v_pk_mul_f32 v[42:43], v[20:21], v[42:43] op_sel_hi:[0,1]
	v_pk_mul_f32 v[40:41], v[20:21], v[40:41] op_sel_hi:[0,1]
	v_pk_mul_f32 v[46:47], v[20:21], v[24:25] op_sel_hi:[0,1]
	v_pk_mul_f32 v[20:21], v[20:21], v[26:27] op_sel_hi:[0,1]
	s_waitcnt vmcnt(3)
	v_pk_mul_f32 v[26:27], v[10:11], v[38:39]
	s_waitcnt vmcnt(2)
	v_mul_f32_e32 v18, v16, v36
	v_pk_mul_f32 v[24:25], v[12:13], v[22:23]
	s_waitcnt vmcnt(0)
	v_mul_f32_e32 v16, v19, v34
	v_mov_b32_e32 v34, v17
	v_pk_mul_f32 v[22:23], v[14:15], v[42:43]
	v_pk_mul_f32 v[14:15], v[28:29], v[40:41]
	v_pk_mul_f32 v[12:13], v[44:45], v[30:31]
	v_pk_mul_f32 v[10:11], v[46:47], v[32:33]
	v_pk_mul_f32 v[20:21], v[34:35], v[20:21]
	s_and_saveexec_b64 s[2:3], s[4:5]
	s_cbranch_execz .LBB0_835
; __device__ __forceinline__ float2 twid(float turns) { return make_float2(__builtin_amdgcn_cosf(turns), __builtin_amdgcn_sinf(turns)); }
; __device__ __forceinline__ void qk_prep_store(u32x4 a, u32x4 b, const float* gain, int sub, int pos, float scale, bf16_t* dst, int lane) {
;     ...
;     if (sub == 0) {
;         const float ihi[8] = {(float)(1.0 / 3.14159265358979323846), (float)(0.19392274474868576 / 3.14159265358979323846), (float)(0.03760603093086393 / 3.14159265358979323846), (float)(0.007292664737217109 / 3.14159265358979323846),
;                               (float)(0.001414213562373095 / 3.14159265358979323846), (float)(0.0002742481756762073 / 3.14159265358979323846), (float)(5.318295896944988e-05 / 3.14159265358979323846), (float)(1.031338537721246e-05 / 3.14159265358979323846)};
;         const float ilo[8] = {(float)(1.0 / 3.14159265358979323846 - (double)(float)(1.0 / 3.14159265358979323846)), (float)(0.19392274474868576 / 3.14159265358979323846 - (double)(float)(0.19392274474868576 / 3.14159265358979323846)),
;                               (float)(0.03760603093086393 / 3.14159265358979323846 - (double)(float)(0.03760603093086393 / 3.14159265358979323846)), (float)(0.007292664737217109 / 3.14159265358979323846 - (double)(float)(0.007292664737217109 / 3.14159265358979323846)),
;                               (float)(0.001414213562373095 / 3.14159265358979323846 - (double)(float)(0.001414213562373095 / 3.14159265358979323846)), (float)(0.0002742481756762073 / 3.14159265358979323846 - (double)(float)(0.0002742481756762073 / 3.14159265358979323846)),
;                               (float)(5.318295896944988e-05 / 3.14159265358979323846 - (double)(float)(5.318295896944988e-05 / 3.14159265358979323846)), (float)(1.031338537721246e-05 / 3.14159265358979323846 - (double)(float)(1.031338537721246e-05 / 3.14159265358979323846))};
; #pragma unroll
;         for (int j = 0; j < 8; ++j) {
;             const float fp = (float)pos, ph = fp * ihi[j], pe = __builtin_fmaf(fp, ihi[j], -ph) + fp * ilo[j];
;             const float red = (ph - 2.0f * rintf(0.5f * ph)) + pe;
;             const float2 cs = twid(0.5f * red); const float c = cs.x, s = cs.y;
;             const float x1 = x[j], x2 = x[8 + j];
;             x[j] = x1 * c - x2 * s; x[8 + j] = x2 * c + x1 * s;
;         }
;     }
	v_cvt_f32_i32_e32 v28, v84
	s_mov_b32 s16, 0x3ea2f983
	s_mov_b32 s15, 0x3d7cd601
	v_readlane_b32 s36, v254, 14
	v_mul_f32_e32 v17, 0x3ea2f983, v28
	v_mul_f32_e32 v29, 0.5, v17
	v_fma_f32 v19, v28, s16, -v17
	v_rndne_f32_e32 v29, v29
	v_fmac_f32_e32 v19, 0x325c9c88, v28
	v_fmac_f32_e32 v17, -2.0, v29
	v_add_f32_e32 v17, v19, v17
	v_mul_f32_e32 v17, 0.5, v17
	v_mul_f32_e32 v35, 0x3d7cd601, v28
	v_cos_f32_e32 v30, v17
	v_sin_f32_e32 v32, v17
	v_mul_f32_e32 v17, 0.5, v35
	s_mov_b32 s16, 0xb045cd43
	v_fma_f32 v34, v28, s15, -v35
	v_rndne_f32_e32 v29, v17
	s_mov_b32 s17, -2.0
	v_pk_fma_f32 v[34:35], v[28:29], s[16:17], v[34:35]
	s_mov_b32 s15, 0x3c441f60
	v_add_f32_e32 v17, v34, v35
	v_mul_f32_e32 v17, 0.5, v17
	v_sin_f32_e32 v33, v17
	v_cos_f32_e32 v31, v17
	v_mul_f32_e32 v17, 0x3c441f60, v28
	v_fma_f32 v19, v28, s15, -v17
	v_pk_mul_f32 v[34:35], v[32:33], v[14:15]
	v_fmac_f32_e32 v19, 0x2fe5870b, v28
	v_pk_fma_f32 v[34:35], v[30:31], v[26:27], v[34:35] neg_lo:[0,0,1] neg_hi:[0,0,1]
	v_pk_mul_f32 v[26:27], v[32:33], v[26:27]
	v_mul_f32_e32 v33, 0x3b182169, v28
	v_pk_fma_f32 v[14:15], v[30:31], v[14:15], v[26:27]
	v_mul_f32_e32 v26, 0.5, v17
	v_rndne_f32_e32 v26, v26
	v_fmac_f32_e32 v17, -2.0, v26
	v_add_f32_e32 v17, v19, v17
	v_mul_f32_e32 v17, 0.5, v17
	v_cos_f32_e32 v26, v17
	v_sin_f32_e32 v30, v17
	s_mov_b32 s15, 0x3b182169
	v_mul_f32_e32 v17, 0.5, v33
	v_readlane_b32 s37, v254, 15
	v_fma_f32 v32, v28, s15, -v33
	v_rndne_f32_e32 v29, v17
	s_mov_b32 s37, s17
	v_pk_fma_f32 v[32:33], v[28:29], s[36:37], v[32:33]
	s_mov_b32 s16, s36
	v_add_f32_e32 v17, v32, v33
	v_mul_f32_e32 v17, 0.5, v17
	v_cos_f32_e32 v27, v17
	v_sin_f32_e32 v31, v17
	v_writelane_b32 v254, s16, 14
	s_mov_b32 s15, 0x39ec0335
	v_pk_mul_f32 v[32:33], v[30:31], v[12:13]
	v_writelane_b32 v254, s17, 15
	v_pk_mul_f32 v[12:13], v[26:27], v[12:13]
	v_pk_fma_f32 v[32:33], v[26:27], v[24:25], v[32:33] neg_lo:[0,0,1] neg_hi:[0,0,1]
	v_pk_fma_f32 v[12:13], v[30:31], v[24:25], v[12:13]
	v_mul_f32_e32 v25, 0x39ec0335, v28
	v_readlane_b32 s36, v254, 16
	v_mul_f32_e32 v17, 0.5, v25
	v_readlane_b32 s37, v254, 17
	v_fma_f32 v24, v28, s15, -v25
	v_rndne_f32_e32 v29, v17
	s_mov_b32 s37, s17
	s_mov_b32 s16, s36
	v_pk_fma_f32 v[24:25], v[28:29], s[36:37], v[24:25]
	v_writelane_b32 v254, s16, 16
	v_add_f32_e32 v17, v24, v25
	v_mul_f32_e32 v17, 0.5, v17
	v_writelane_b32 v254, s17, 17
	v_mul_f32_e32 v31, 0x38b712a2, v28
	v_cos_f32_e32 v24, v17
	v_sin_f32_e32 v26, v17
	s_mov_b32 s15, 0x38b712a2
	v_mul_f32_e32 v17, 0.5, v31
	v_readlane_b32 s36, v254, 18
	v_fma_f32 v30, v28, s15, -v31
	v_rndne_f32_e32 v29, v17
	s_mov_b32 s16, s36
	v_pk_fma_f32 v[30:31], v[28:29], s[16:17], v[30:31]
	s_mov_b32 s15, 0x378e0206
	v_add_f32_e32 v17, v30, v31
	v_mul_f32_e32 v17, 0.5, v17
	v_cos_f32_e32 v25, v17
	v_sin_f32_e32 v27, v17
	v_mul_f32_e32 v17, 0x378e0206, v28
	v_fma_f32 v19, v28, s15, -v17
	v_fmac_f32_e32 v19, 0x2a947bf1, v28
	v_pk_mul_f32 v[30:31], v[26:27], v[10:11]
	v_pk_mul_f32 v[10:11], v[24:25], v[10:11]
	v_pk_fma_f32 v[30:31], v[24:25], v[22:23], v[30:31] neg_lo:[0,0,1] neg_hi:[0,0,1]
	v_pk_fma_f32 v[10:11], v[26:27], v[22:23], v[10:11]
	v_mul_f32_e32 v22, 0.5, v17
	v_rndne_f32_e32 v22, v22
	v_fmac_f32_e32 v17, -2.0, v22
	v_add_f32_e32 v17, v19, v17
	v_mul_f32_e32 v17, 0.5, v17
	v_cos_f32_e32 v22, v17
	v_sin_f32_e32 v24, v17
	v_mul_f32_e32 v17, 0x365c4efa, v28
	s_mov_b32 s15, 0x365c4efa
	v_mul_f32_e32 v23, 0.5, v17
	v_fma_f32 v19, v28, s15, -v17
	v_rndne_f32_e32 v23, v23
	v_fmac_f32_e32 v19, 0x28c5eb61, v28
	v_fmac_f32_e32 v17, -2.0, v23
	v_add_f32_e32 v17, v19, v17
	v_mul_f32_e32 v17, 0.5, v17
	v_sin_f32_e32 v25, v17
	v_cos_f32_e32 v23, v17
	v_mov_b32_e32 v17, v21
	v_mul_f32_e32 v26, v22, v16
	v_mov_b32_e32 v19, v20
	v_pk_mul_f32 v[16:17], v[24:25], v[16:17]
	v_mul_f32_e32 v36, v24, v18
	v_pk_fma_f32 v[18:19], v[22:23], v[18:19], v[16:17] neg_lo:[0,0,1] neg_hi:[0,0,1]
	v_mov_b32_e32 v22, v25
	v_pk_mul_f32 v[16:17], v[22:23], v[20:21]
	v_readlane_b32 s37, v254, 19
	v_mov_b32_e32 v37, v16
	v_mov_b32_e32 v27, v17
	v_writelane_b32 v254, s36, 18
	v_pk_add_f32 v[16:17], v[36:37], v[26:27]
	v_mov_b32_e32 v26, v34
	v_writelane_b32 v254, s37, 19
	v_mov_b32_e32 v27, v35
	v_mov_b32_e32 v24, v32
	v_mov_b32_e32 v25, v33
	v_mov_b32_e32 v22, v30
	v_mov_b32_e32 v23, v31
	v_mov_b32_e32 v20, v19
	v_mov_b32_e32 v21, v17

; __device__ __forceinline__ void ph_attn(KP p, int l, unsigned char* sm, int wv) {
;     ...
;                 float sv[2][4]; float mx = -1e30f;
;                 if (interior && s >= 1 && s <= 7) {
; #pragma unroll
;                     for (int kt = 0; kt < 2; ++kt)
; #pragma unroll
;                         for (int r = 0; r < 4; ++r) { sv[kt][r] = st[kt][r]; mx = fmaxf(mx, sv[kt][r]); }
;                 } else {
; #pragma unroll
;                     for (int kt = 0; kt < 2; ++kt)
; #pragma unroll
;                         for (int r = 0; r < 4; ++r) {
;                             const int kk = kk0 + 16 * kt + 4 * fq + r, d = kk - 128 - qi, prel = Q0rel + kk - 128;
;                             const bool valid = d >= -128 && d <= 128 && prel >= 0 && prel < L && kk < 384;
;                             sv[kt][r] = valid ? st[kt][r] : -1e30f;
;                             mx = fmaxf(mx, sv[kt][r]);
;                         }
;                 }
;                 mx = fmaxf(mx, shx(mx, 16, lane)); mx = fmaxf(mx, shx(mx, 32, lane));
;                 const float mn = fmaxf(mrun, mx), alpha = __builtin_amdgcn_exp2f(mrun - mn);
;                 mrun = mn;
;                 float pr[2][4], psum = 0.f;
; #pragma unroll
;                 for (int kt = 0; kt < 2; ++kt)
; #pragma unroll
;                     for (int r = 0; r < 4; ++r) { pr[kt][r] = __builtin_amdgcn_exp2f(sv[kt][r] - mn); psum += pr[kt][r]; }
;                 lsum = lsum * alpha + psum;
;                 const bool rescale = __builtin_amdgcn_ballot_w64(alpha != 1.0f) != 0ull;
;                 union { bf16x8 v; unsigned u[4]; } pf;
;                 pf.u[0] = pk2(pr[0][0], pr[0][1]); pf.u[1] = pk2(pr[0][2], pr[0][3]); pf.u[2] = pk2(pr[1][0], pr[1][1]); pf.u[3] = pk2(pr[1][2], pr[1][3]);
; #pragma unroll
;                 for (int dt = 0; dt < 4; ++dt) {
;                     if (rescale) o[dt] = o[dt] * alpha;
;                     union { bf16x8 v; u32x2 h[2]; } vf;
;                     vf.h[0] = *(const u32x2*)(Vt + (16 * dt + fr) * 404 + kk0 + 4 * fq);
;                     vf.h[1] = *(const u32x2*)(Vt + (16 * dt + fr) * 404 + kk0 + 16 + 4 * fq);
;                     o[dt] = __builtin_amdgcn_mfma_f32_16x16x32_bf16(vf.v, pf.v, o[dt], 0, 0, 0);
;                 }
;             }
;             lsum += shx(lsum, 16, lane); lsum += shx(lsum, 32, lane);
;             const float il = frcp(lsum);
.LBB0_837:
	ds_read_b128 v[160:163], v157
	ds_read_b128 v[164:167], v157 offset:64
	ds_read_b128 v[224:227], v157 offset:2304
	ds_read_b128 v[182:185], v157 offset:2368
	ds_read2_b64 v[186:189], v159 offset0:96 offset1:100
	ds_read2_b64 v[190:193], v141 offset1:4
	ds_read2_b64 v[194:197], v142 offset1:4
	ds_read2_b64 v[198:201], v143 offset1:4
	s_waitcnt lgkmcnt(7)
	v_mfma_f32_16x16x32_bf16 v[160:163], v[160:163], v[38:41], 0
	s_waitcnt lgkmcnt(6)
	v_mfma_f32_16x16x32_bf16 v[160:163], v[164:167], v[34:37], v[160:163]
	s_waitcnt lgkmcnt(5)
	v_mfma_f32_16x16x32_bf16 v[38:41], v[224:227], v[38:41], 0
	s_nop 5
	v_cndmask_b32_e64 v59, v243, v163, s[78:79]
	s_waitcnt lgkmcnt(4)
	v_mfma_f32_16x16x32_bf16 v[34:37], v[182:185], v[34:37], v[38:41]
	s_nop 2
	v_cndmask_b32_e64 v38, v243, v160, s[72:73]
	v_cndmask_b32_e64 v39, v243, v161, s[74:75]
	v_max3_f32 v40, v38, s35, v39
	v_cndmask_b32_e64 v41, v243, v162, s[76:77]
	v_max3_f32 v40, v40, v41, v59
	v_cndmask_b32_e64 v34, v243, v34, s[80:81]
	v_cndmask_b32_e64 v35, v243, v35, s[82:83]
	v_max3_f32 v40, v40, v34, v35
	v_cndmask_b32_e64 v36, v243, v36, s[84:85]
	v_cndmask_b32_e64 v37, v243, v37, s[86:87]
	v_max3_f32 v40, v40, v36, v37
	v_mov_b32_e32 v60, v40
	s_nop 1
	v_permlane16_swap_b32_e32 v40, v60
	s_nop 0
	s_waitcnt lgkmcnt(0)
	v_max_f32_e32 v60, v60, v60
	v_max_f32_e32 v40, v40, v60
	v_mov_b32_e32 v60, v40
	s_nop 1
	v_permlane32_swap_b32_e32 v40, v60
	s_nop 0
	s_waitcnt lgkmcnt(0)
	v_max3_f32 v40, v63, v40, v60
	v_sub_f32_e32 v38, v38, v40
	v_exp_f32_e32 v61, v38
	v_sub_f32_e32 v39, v39, v40
	v_exp_f32_e32 v39, v39
	v_sub_f32_e32 v41, v41, v40
	v_exp_f32_e32 v41, v41
	v_sub_f32_e32 v59, v59, v40
	v_exp_f32_e32 v59, v59
	v_add_f32_e32 v38, 0, v61
	v_add_f32_e32 v38, v39, v38
	v_sub_f32_e32 v60, v63, v40
	v_add_f32_e32 v38, v41, v38
	v_add_f32_e32 v64, v59, v38
	v_exp_f32_e32 v38, v60
	v_sub_f32_e32 v34, v34, v40
	v_exp_f32_e32 v65, v34
	v_sub_f32_e32 v34, v35, v40
	v_exp_f32_e32 v160, v34
	v_sub_f32_e32 v34, v36, v40
	v_cmp_neq_f32_e32 vcc, 1.0, v38
	v_exp_f32_e32 v161, v34
	v_sub_f32_e32 v34, v37, v40
	s_cmp_eq_u64 vcc, 0
	v_exp_f32_e32 v162, v34
	s_cselect_b64 vcc, -1, 0
	v_pk_mul_f32 v[34:35], v[46:47], v[38:39] op_sel_hi:[1,0]
	v_pk_mul_f32 v[36:37], v[48:49], v[38:39] op_sel_hi:[1,0]
	v_cvt_pk_bf16_f32 v60, v61, v39
	v_cvt_pk_bf16_f32 v61, v41, v59
	v_cvt_pk_bf16_f32 v62, v65, v160
	v_cvt_pk_bf16_f32 v63, v161, v162
	v_cndmask_b32_e32 v35, v35, v47, vcc
	v_cndmask_b32_e32 v37, v37, v49, vcc
	v_cndmask_b32_e32 v36, v36, v48, vcc
	v_cndmask_b32_e32 v34, v34, v46, vcc
	v_pk_mul_f32 v[40:41], v[38:39], v[52:53] op_sel_hi:[0,1]
	s_waitcnt lgkmcnt(0)
	v_mfma_f32_16x16x32_bf16 v[34:37], v[186:189], v[60:63], v[34:37]
	v_mul_f32_e64 v46, v38, v50
	v_mul_f32_e64 v47, v38, v51
	v_cndmask_b32_e32 v49, v41, v53, vcc
	v_cndmask_b32_e32 v48, v40, v52, vcc
	v_cndmask_b32_e32 v47, v47, v51, vcc
	v_cndmask_b32_e32 v46, v46, v50, vcc
	v_pk_mul_f32 v[40:41], v[38:39], v[44:45] op_sel_hi:[0,1]
	s_nop 0
	v_mfma_f32_16x16x32_bf16 v[46:49], v[190:193], v[60:63], v[46:49]
	v_mul_f32_e64 v50, v38, v42
	v_mul_f32_e64 v51, v38, v43
	v_cndmask_b32_e32 v43, v51, v43, vcc
	v_cndmask_b32_e32 v42, v50, v42, vcc
	v_cndmask_b32_e32 v45, v41, v45, vcc
	v_cndmask_b32_e32 v44, v40, v44, vcc
	s_add_i32 s39, s39, 1
	s_nop 0
	v_mfma_f32_16x16x32_bf16 v[40:43], v[194:197], v[60:63], v[42:45]
	s_nop 2
	v_mul_f32_e64 v44, v38, v56
	v_mul_f32_e64 v45, v38, v57
	v_pk_mul_f32 v[50:51], v[38:39], v[54:55] op_sel_hi:[0,1]
	v_add_f32_e32 v39, v65, v64
	v_add_f32_e32 v39, v160, v39
	v_add_f32_e32 v39, v161, v39
	v_add_f32_e32 v39, v162, v39
	v_fmac_f32_e32 v39, v58, v38
	v_mov_b32_e32 v38, v39
	s_nop 1
	v_permlane16_swap_b32_e32 v39, v38
	s_nop 0
	v_cndmask_b32_e32 v53, v45, v57, vcc
	v_cndmask_b32_e32 v52, v44, v56, vcc
	v_cndmask_b32_e32 v51, v51, v55, vcc
	v_cndmask_b32_e32 v50, v50, v54, vcc
	s_waitcnt lgkmcnt(0)
	v_add_f32_e32 v38, v39, v38
	v_mov_b32_e32 v39, v38
	s_nop 1
	v_permlane32_swap_b32_e32 v38, v39
	s_nop 0
	s_waitcnt lgkmcnt(0)
	v_mfma_f32_16x16x32_bf16 v[50:53], v[198:201], v[60:63], v[50:53]
	v_add_f32_e32 v38, v38, v39
	v_div_scale_f32 v39, s[2:3], v38, v38, 1.0
	v_rcp_f32_e32 v44, v39
	v_readlane_b32 s2, v254, 22
	v_readlane_b32 s3, v254, 23
	s_load_dwordx2 s[2:3], s[2:3], 0xf8
	v_fma_f32 v45, -v39, v44, 1.0
	v_fmac_f32_e32 v44, v45, v44
	v_div_scale_f32 v45, vcc, 1.0, v38, 1.0
	v_mul_f32_e32 v54, v45, v44
	v_fma_f32 v55, -v39, v54, v45
	v_fmac_f32_e32 v54, v55, v44
	v_fma_f32 v39, -v39, v54, v45
	v_div_fmas_f32 v39, v39, v44, v54
	v_div_fixup_f32 v44, v39, v38, 1.0
	s_waitcnt lgkmcnt(0)
	v_lshl_add_u64 v[38:39], s[2:3], 0, v[92:93]
	s_lshl_b32 s2, s40, 6
	s_ashr_i32 s3, s2, 31
	v_mul_f32_e32 v34, v44, v34
	v_mul_f32_e32 v35, v44, v35
	v_lshl_add_u64 v[38:39], s[2:3], 1, v[38:39]
	v_cvt_pk_bf16_f32 v34, v34, v35
	v_mul_f32_e32 v35, v44, v36
	v_lshl_add_u64 v[38:39], v[38:39], 0, v[0:1]
	v_mul_f32_e32 v36, v44, v37
	v_cvt_pk_bf16_f32 v35, v35, v36
	global_store_dwordx2 v[38:39], v[34:35], off
	v_mul_f32_e32 v34, v44, v46
	v_mul_f32_e32 v35, v44, v47
	v_cvt_pk_bf16_f32 v34, v34, v35
	v_mul_f32_e32 v35, v44, v48
	v_mul_f32_e32 v36, v44, v49
	v_cvt_pk_bf16_f32 v35, v35, v36
	global_store_dwordx2 v[38:39], v[34:35], off offset:32
	v_mul_f32_e32 v34, v44, v40
	v_mul_f32_e32 v35, v44, v41
	v_cvt_pk_bf16_f32 v34, v34, v35
	v_mul_f32_e32 v35, v44, v42
	v_mul_f32_e32 v36, v44, v43
	v_cvt_pk_bf16_f32 v35, v35, v36
	global_store_dwordx2 v[38:39], v[34:35], off offset:64
	v_mul_f32_e32 v34, v50, v44
	v_mul_f32_e32 v35, v51, v44
	v_cvt_pk_bf16_f32 v34, v34, v35
	v_mul_f32_e32 v35, v52, v44
	s_cmp_eq_u32 s39, 4
	v_mul_f32_e32 v36, v53, v44
	v_cvt_pk_bf16_f32 v35, v35, v36
	global_store_dwordx2 v[38:39], v[34:35], off offset:96
	s_cbranch_scc1 .LBB0_809

; __device__ __forceinline__ void qk_prep_store(u32x4 a, u32x4 b, const float* gain, int sub, int pos, float scale, bf16_t* dst, int lane) {
;     float x[16]; unpack16(a, b, x);
;     float ss = 0.f;
; #pragma unroll
;     for (int i = 0; i < 16; ++i) ss += x[i] * x[i];
;     ss += shx(ss, 1, lane); ss += shx(ss, 2, lane);
;     const float r = rsqrtf(ss * (1.0f / 64.0f) + EPS);
; #pragma unroll
;     for (int i = 0; i < 16; ++i) x[i] = x[i] * r * gain[sub * 16 + i];
;     if (sub == 0) {
;         const float ihi[8] = {(float)(1.0 / 3.14159265358979323846), (float)(0.19392274474868576 / 3.14159265358979323846), (float)(0.03760603093086393 / 3.14159265358979323846), (float)(0.007292664737217109 / 3.14159265358979323846),
;                               (float)(0.001414213562373095 / 3.14159265358979323846), (float)(0.0002742481756762073 / 3.14159265358979323846), (float)(5.318295896944988e-05 / 3.14159265358979323846), (float)(1.031338537721246e-05 / 3.14159265358979323846)};
;         const float ilo[8] = {(float)(1.0 / 3.14159265358979323846 - (double)(float)(1.0 / 3.14159265358979323846)), (float)(0.19392274474868576 / 3.14159265358979323846 - (double)(float)(0.19392274474868576 / 3.14159265358979323846)),
;                               (float)(0.03760603093086393 / 3.14159265358979323846 - (double)(float)(0.03760603093086393 / 3.14159265358979323846)), (float)(0.007292664737217109 / 3.14159265358979323846 - (double)(float)(0.007292664737217109 / 3.14159265358979323846)),
;                               (float)(0.001414213562373095 / 3.14159265358979323846 - (double)(float)(0.001414213562373095 / 3.14159265358979323846)), (float)(0.0002742481756762073 / 3.14159265358979323846 - (double)(float)(0.0002742481756762073 / 3.14159265358979323846)),
;                               (float)(5.318295896944988e-05 / 3.14159265358979323846 - (double)(float)(5.318295896944988e-05 / 3.14159265358979323846)), (float)(1.031338537721246e-05 / 3.14159265358979323846 - (double)(float)(1.031338537721246e-05 / 3.14159265358979323846))};
; #pragma unroll
;         for (int j = 0; j < 8; ++j) {
;             const float fp = (float)pos, ph = fp * ihi[j], pe = __builtin_fmaf(fp, ihi[j], -ph) + fp * ilo[j];
;             const float red = (ph - 2.0f * rintf(0.5f * ph)) + pe;
;             const float2 cs = twid(0.5f * red); const float c = cs.x, s = cs.y;
.LBB0_844:
	global_load_dwordx4 v[42:45], v[72:73], off
	global_load_dwordx4 v[52:55], v[72:73], off offset:16
	global_load_dwordx4 v[56:59], v[72:73], off offset:32
	global_load_dwordx4 v[60:63], v[72:73], off offset:48
	v_lshlrev_b32_e32 v48, 16, v34
	v_and_b32_e32 v49, 0xffff0000, v34
	v_lshlrev_b32_e32 v34, 16, v35
	v_and_b32_e32 v35, 0xffff0000, v35
	v_pk_mul_f32 v[160:161], v[48:49], v[48:49]
	v_pk_mul_f32 v[164:165], v[34:35], v[34:35]
	v_add_f32_e32 v160, v160, v161
	v_lshlrev_b32_e32 v64, 16, v36
	v_and_b32_e32 v65, 0xffff0000, v36
	v_add_f32_e32 v160, v164, v160
	v_pk_mul_f32 v[168:169], v[64:65], v[64:65]
	v_add_f32_e32 v160, v165, v160
	v_add_f32_e32 v160, v168, v160
	v_lshlrev_b32_e32 v159, 16, v37
	v_add_f32_e32 v160, v169, v160
	v_and_b32_e32 v172, 0xffff0000, v37
	v_lshlrev_b32_e32 v50, 16, v38
	v_and_b32_e32 v51, 0xffff0000, v38
	v_fmac_f32_e32 v160, v159, v159
	v_pk_mul_f32 v[162:163], v[50:51], v[50:51]
	v_fmac_f32_e32 v160, v172, v172
	v_lshlrev_b32_e32 v38, 16, v39
	v_and_b32_e32 v39, 0xffff0000, v39
	v_add_f32_e32 v160, v160, v162
	v_pk_mul_f32 v[166:167], v[38:39], v[38:39]
	v_add_f32_e32 v160, v163, v160
	v_lshlrev_b32_e32 v36, 16, v40
	v_and_b32_e32 v37, 0xffff0000, v40
	v_add_f32_e32 v160, v166, v160
	v_pk_mul_f32 v[170:171], v[36:37], v[36:37]
	v_add_f32_e32 v160, v167, v160
	v_and_b32_e32 v46, 0xffff0000, v41
	v_lshlrev_b32_e32 v47, 16, v41
	v_add_f32_e32 v160, v170, v160
	v_pk_mul_f32 v[40:41], v[46:47], v[46:47]
	v_add_f32_e32 v160, v171, v160
	v_add_f32_e32 v41, v41, v160
	v_add_f32_e32 v40, v40, v41
	s_nop 1
	v_mov_b32_dpp v41, v40 quad_perm:[1,0,3,2] row_mask:0xf bank_mask:0xf
	s_mov_b32 s2, 0x800000
	s_waitcnt lgkmcnt(0)
	v_add_f32_e32 v40, v40, v41
	s_nop 1
	v_mov_b32_dpp v41, v40 quad_perm:[2,3,0,1] row_mask:0xf bank_mask:0xf
	s_waitcnt lgkmcnt(0)
	v_add_f32_e32 v40, v40, v41
	v_fmamk_f32 v40, v40, 0x3c800000, v205
	v_mul_f32_e32 v41, 0x4b800000, v40
	v_cmp_gt_f32_e32 vcc, s2, v40
	s_nop 1
	v_cndmask_b32_e32 v40, v40, v41, vcc
	v_rsq_f32_e32 v40, v40
	s_nop 0
	v_mul_f32_e32 v41, 0x45800000, v40
	v_cndmask_b32_e32 v40, v40, v41, vcc
	v_pk_mul_f32 v[48:49], v[40:41], v[48:49] op_sel_hi:[0,1]
	v_pk_mul_f32 v[34:35], v[40:41], v[34:35] op_sel_hi:[0,1]
	v_pk_mul_f32 v[64:65], v[40:41], v[64:65] op_sel_hi:[0,1]
	v_mul_f32_e32 v41, v40, v159
	v_mul_f32_e32 v159, v40, v47
	v_mov_b32_e32 v47, v172
	v_pk_mul_f32 v[160:161], v[40:41], v[50:51] op_sel_hi:[0,1]
	v_pk_mul_f32 v[162:163], v[40:41], v[38:39] op_sel_hi:[0,1]
	v_pk_mul_f32 v[164:165], v[40:41], v[36:37] op_sel_hi:[0,1]
	v_pk_mul_f32 v[166:167], v[40:41], v[46:47] op_sel_hi:[0,1]
	s_waitcnt vmcnt(3)
	v_pk_mul_f32 v[50:51], v[42:43], v[48:49]
	s_waitcnt vmcnt(2)
	v_mul_f32_e32 v42, v54, v41
	v_pk_mul_f32 v[48:49], v[44:45], v[34:35]
	s_waitcnt vmcnt(0)
	v_mov_b32_e32 v54, v63
	v_pk_mul_f32 v[46:47], v[52:53], v[64:65]
	v_pk_mul_f32 v[38:39], v[56:57], v[160:161]
	v_pk_mul_f32 v[36:37], v[58:59], v[162:163]
	v_pk_mul_f32 v[34:35], v[60:61], v[164:165]
	v_mul_f32_e32 v40, v62, v159
	v_pk_mul_f32 v[44:45], v[54:55], v[166:167]
	s_and_saveexec_b64 s[2:3], s[4:5]
	s_cbranch_execz .LBB0_846
	v_pk_mul_f32 v[52:53], v[76:77], v[38:39]
	v_mov_b32_e32 v41, v44
	v_pk_fma_f32 v[52:53], v[74:75], v[50:51], v[52:53] neg_lo:[0,0,1] neg_hi:[0,0,1]
	v_pk_mul_f32 v[50:51], v[76:77], v[50:51]
	v_mov_b32_e32 v43, v45
	v_pk_fma_f32 v[38:39], v[74:75], v[38:39], v[50:51]
	v_pk_mul_f32 v[50:51], v[80:81], v[36:37]
	s_nop 0
	v_pk_fma_f32 v[54:55], v[78:79], v[48:49], v[50:51] neg_lo:[0,0,1] neg_hi:[0,0,1]
	v_pk_mul_f32 v[48:49], v[80:81], v[48:49]
	v_mov_b32_e32 v50, v52
	v_pk_fma_f32 v[36:37], v[78:79], v[36:37], v[48:49]
	v_pk_mul_f32 v[48:49], v[84:85], v[34:35]
	v_mov_b32_e32 v51, v53
	v_pk_fma_f32 v[56:57], v[82:83], v[46:47], v[48:49] neg_lo:[0,0,1] neg_hi:[0,0,1]
	v_pk_mul_f32 v[46:47], v[84:85], v[46:47]
	v_mul_f32_e32 v48, v88, v42
	v_pk_fma_f32 v[34:35], v[82:83], v[34:35], v[46:47]
	v_mul_f32_e32 v46, v86, v40
	v_pk_mul_f32 v[40:41], v[88:89], v[40:41]
	s_nop 0
	v_pk_fma_f32 v[42:43], v[86:87], v[42:43], v[40:41] neg_lo:[0,0,1] neg_hi:[0,0,1]
	v_pk_mul_f32 v[40:41], v[90:91], v[44:45]
	v_mov_b32_e32 v45, v43
	v_mov_b32_e32 v47, v40
	v_mov_b32_e32 v49, v41
	v_pk_add_f32 v[40:41], v[46:47], v[48:49]
	v_mov_b32_e32 v48, v54
	v_mov_b32_e32 v49, v55
	v_mov_b32_e32 v46, v56
	v_mov_b32_e32 v47, v57
	v_mov_b32_e32 v44, v41
; __device__ __forceinline__ void qk_prep_store(u32x4 a, u32x4 b, const float* gain, int sub, int pos, float scale, bf16_t* dst, int lane) {
;     ...
;     u32x4 o0, o1;
;     o0.x = pk2(x[0] * scale, x[1] * scale); o0.y = pk2(x[2] * scale, x[3] * scale); o0.z = pk2(x[4] * scale, x[5] * scale); o0.w = pk2(x[6] * scale, x[7] * scale);
;     o1.x = pk2(x[8] * scale, x[9] * scale); o1.y = pk2(x[10] * scale, x[11] * scale); o1.z = pk2(x[12] * scale, x[13] * scale); o1.w = pk2(x[14] * scale, x[15] * scale);
;     *(u32x4*)dst = o0; *(u32x4*)(dst + 8) = o1;
; __device__ __forceinline__ void ph_attn(KP p, int l, unsigned char* sm, int wv) {
;     ...
;             __syncthreads();
;             bf16x8 qf[2];
; #pragma unroll
;             for (int ks = 0; ks < 2; ++ks) qf[ks] = *(const bf16x8*)(Qs + (16 * wid + fr) * 72 + 32 * ks + 8 * fq);
;             f32x4 o[4];
; #pragma unroll
;             for (int dt = 0; dt < 4; ++dt) o[dt] = (f32x4){0.f, 0.f, 0.f, 0.f};
;             float mrun = p->sink[l * 8 + h] * 1.4426950408889634f;
;             float lsum = fq == 0 ? 1.0f : 0.0f;
;             const int qi = 16 * wid + fr;
;             for (int s = 0; s < 9; ++s) {
;                 const int kk0 = 16 * wid + 32 * s;
;                 f32x4 st[2];
; #pragma unroll
;                 for (int kt = 0; kt < 2; ++kt) {
;                     st[kt] = (f32x4){0.f, 0.f, 0.f, 0.f};
; #pragma unroll
;                     for (int ks = 0; ks < 2; ++ks) {
;                         const bf16x8 kf = *(const bf16x8*)(Ks + (kk0 + 16 * kt + fr) * 72 + 32 * ks + 8 * fq);
;                         st[kt] = __builtin_amdgcn_mfma_f32_16x16x32_bf16(kf, qf[ks], st[kt], 0, 0, 0);
;                     }
;                 }
;                 float sv[2][4]; float mx = -1e30f;
;                 if (interior && s >= 1 && s <= 7) {
; #pragma unroll
;                     for (int kt = 0; kt < 2; ++kt)
; #pragma unroll
;                         for (int r = 0; r < 4; ++r) { sv[kt][r] = st[kt][r]; mx = fmaxf(mx, sv[kt][r]); }
;                 } else {
; #pragma unroll
;                     for (int kt = 0; kt < 2; ++kt)
; #pragma unroll
;                         for (int r = 0; r < 4; ++r) {
;                             const int kk = kk0 + 16 * kt + 4 * fq + r, d = kk - 128 - qi, prel = Q0rel + kk - 128;
.LBB0_846:
	s_or_b64 exec, exec, s[2:3]
	v_mul_f32_e32 v41, 0x3e38aa3b, v50
	v_mul_f32_e32 v43, 0x3e38aa3b, v51
	v_cvt_pk_bf16_f32 v50, v41, v43
	v_mul_f32_e32 v41, 0x3e38aa3b, v48
	v_mul_f32_e32 v43, 0x3e38aa3b, v49
	v_cvt_pk_bf16_f32 v51, v41, v43
	v_mul_f32_e32 v41, 0x3e38aa3b, v46
	v_mul_f32_e32 v34, 0x3e38aa3b, v34
	v_mul_f32_e32 v35, 0x3e38aa3b, v35
	v_readlane_b32 s2, v254, 22
	v_mul_f32_e32 v43, 0x3e38aa3b, v47
	v_cvt_pk_bf16_f32 v52, v41, v43
	v_mul_f32_e32 v41, 0x3e38aa3b, v42
	v_mul_f32_e32 v42, 0x3e38aa3b, v45
	v_cvt_pk_bf16_f32 v53, v41, v42
	v_mul_f32_e32 v38, 0x3e38aa3b, v38
	v_mul_f32_e32 v39, 0x3e38aa3b, v39
	v_cvt_pk_bf16_f32 v46, v38, v39
	v_mul_f32_e32 v36, 0x3e38aa3b, v36
	v_mul_f32_e32 v37, 0x3e38aa3b, v37
	v_cvt_pk_bf16_f32 v47, v36, v37
	v_cvt_pk_bf16_f32 v48, v34, v35
	v_mul_f32_e32 v34, 0x3e38aa3b, v40
	v_mul_f32_e32 v35, 0x3e38aa3b, v44
	v_readlane_b32 s3, v254, 23
	v_cvt_pk_bf16_f32 v49, v34, v35
	ds_write_b128 v98, v[50:53]
	ds_write_b128 v98, v[46:49] offset:16
	s_waitcnt lgkmcnt(0)
	s_barrier
	ds_read_b128 v[38:41], v156
	ds_read_b128 v[34:37], v156 offset:64
	s_load_dwordx2 s[2:3], s[2:3], 0x40
	s_add_i32 s40, s39, s38
	s_add_i32 s18, s40, s31
	s_ashr_i32 s19, s18, 31
	s_lshl_b64 s[18:19], s[18:19], 2
	s_waitcnt lgkmcnt(0)
	s_add_u32 s2, s2, s18
	s_addc_u32 s3, s3, s19
	global_load_dword v54, v1, s[2:3]
	v_add_u32_e32 v50, v102, v100
	ds_read_b128 v[42:45], v50
	ds_read_b128 v[46:49], v50 offset:64
	ds_read_b128 v[224:227], v50 offset:2304
	ds_read_b128 v[182:185], v50 offset:2368
	s_waitcnt lgkmcnt(3)
	v_mfma_f32_16x16x32_bf16 v[42:45], v[42:45], v[38:41], 0
	s_mov_b32 s2, 0x3fb8aa3b
	v_add_u32_e32 v159, 0xe000, v140
	s_mov_b32 s42, 0
	s_waitcnt lgkmcnt(2)
	v_mfma_f32_16x16x32_bf16 v[42:45], v[46:49], v[34:37], v[42:45]
	ds_read2_b64 v[186:189], v159 offset0:32 offset1:36
	ds_read2_b64 v[198:201], v150 offset1:4
	ds_read2_b64 v[190:193], v148 offset1:4
	ds_read2_b64 v[194:197], v149 offset1:4
	s_waitcnt vmcnt(0)
	v_mul_f32_e32 v55, 0x3fb8aa3b, v54
	s_waitcnt lgkmcnt(5)
	v_mfma_f32_16x16x32_bf16 v[46:49], v[224:227], v[38:41], 0
	s_nop 1
	v_cndmask_b32_e64 v42, v243, v42, s[88:89]
	v_cndmask_b32_e64 v43, v243, v43, s[90:91]
	v_cndmask_b32_e64 v44, v243, v44, s[92:93]
	s_waitcnt lgkmcnt(4)
	v_mfma_f32_16x16x32_bf16 v[46:49], v[182:185], v[34:37], v[46:49]
	v_max3_f32 v50, v42, s35, v43
	v_cndmask_b32_e64 v45, v243, v45, s[94:95]
	v_max3_f32 v50, v50, v44, v45
	s_nop 4
	v_cndmask_b32_e64 v46, v243, v46, s[96:97]
	v_cndmask_b32_e64 v47, v243, v47, s[16:17]
	v_max3_f32 v50, v50, v46, v47
	v_cndmask_b32_e64 v48, v243, v48, s[14:15]
	v_cndmask_b32_e64 v49, v243, v49, s[0:1]
	v_max3_f32 v50, v50, v48, v49
	v_mov_b32_e32 v51, v50
	s_nop 1
	v_permlane16_swap_b32_e32 v50, v51
	s_nop 0
	s_waitcnt lgkmcnt(0)
	v_max_f32_e32 v51, v51, v51
	v_max_f32_e32 v50, v50, v51
	v_mov_b32_e32 v51, v50
	s_nop 1
	v_permlane32_swap_b32_e32 v50, v51
	s_nop 0
	s_waitcnt lgkmcnt(0)
	v_max3_f32 v163, v55, v50, v51
	v_sub_f32_e32 v42, v42, v163
	v_exp_f32_e32 v59, v42
	v_sub_f32_e32 v42, v43, v163
	v_exp_f32_e32 v64, v42
	v_sub_f32_e32 v42, v44, v163
	v_exp_f32_e32 v65, v42
	v_sub_f32_e32 v42, v45, v163
	v_exp_f32_e32 v160, v42
	v_sub_f32_e32 v42, v46, v163
	v_exp_f32_e32 v161, v42
	v_sub_f32_e32 v42, v47, v163
	v_exp_f32_e32 v162, v42
	v_sub_f32_e32 v42, v48, v163
	v_fma_f32 v50, v54, s2, -v163
	v_exp_f32_e32 v168, v42
	v_sub_f32_e32 v42, v49, v163
	v_exp_f32_e32 v169, v42
	v_exp_f32_e32 v58, v50
	v_cvt_pk_bf16_f32 v54, v59, v64
	v_cvt_pk_bf16_f32 v55, v65, v160
	v_cvt_pk_bf16_f32 v56, v161, v162
	v_cvt_pk_bf16_f32 v57, v168, v169
	s_nop 0
	v_cmp_neq_f32_e32 vcc, 1.0, v58
	s_cmp_eq_u64 vcc, 0
	s_cselect_b64 s[2:3], -1, 0
	v_mul_f32_e32 v46, 0, v58
	v_cndmask_b32_e64 v60, v46, 0, s[2:3]
	v_mov_b32_e32 v61, v60
	v_mov_b32_e32 v62, v60
	v_mov_b32_e32 v63, v60
	s_nop 0
	s_waitcnt lgkmcnt(0)
	v_mfma_f32_16x16x32_bf16 v[46:49], v[186:189], v[54:57], v[60:63]
	s_nop 0
	s_waitcnt lgkmcnt(0)
	v_mfma_f32_16x16x32_bf16 v[50:53], v[190:193], v[54:57], v[60:63]
	s_nop 0
	s_waitcnt lgkmcnt(0)
	v_mfma_f32_16x16x32_bf16 v[42:45], v[194:197], v[54:57], v[60:63]
	s_nop 2
	v_mul_f32_e64 v60, v58, 0
	v_mul_f32_e64 v61, v58, 0
	v_add_f32_e32 v59, 0, v59
	v_add_f32_e32 v59, v64, v59
	v_add_f32_e32 v59, v65, v59
	v_cndmask_b32_e64 v61, v61, 0, s[2:3]
	v_cndmask_b32_e64 v60, v60, 0, s[2:3]
	v_add_f32_e32 v59, v160, v59
	v_mov_b32_e32 v62, v60
	v_mov_b32_e32 v63, v61
	v_add_f32_e32 v59, v161, v59
	v_add_f32_e32 v59, v162, v59
	v_mfma_f32_16x16x32_bf16 v[54:57], v[198:201], v[54:57], v[60:63]
	v_add_f32_e32 v59, v168, v59
	v_add_f32_e32 v162, v169, v59
	v_fmac_f32_e32 v162, v101, v58
	v_mov_b32_e32 v160, v152
	v_mov_b32_e32 v161, v151
